# attn_sample: hoist all 8 K-row load pairs before the score loop (on top of SSD precompute + phase A transposes)
# speedup vs baseline: 1.0123x; 1.0116x over previous
; __device__ __forceinline__ float bflo(unsigned w) { return __uint_as_float(w << 16); }
; __device__ __forceinline__ float bfhi(unsigned w) { return __uint_as_float(w & 0xffff0000u); }
; __device__ __forceinline__ int lane_fresh() { int l; asm volatile("v_mbcnt_lo_u32_b32 %0, -1, 0\n\tv_mbcnt_hi_u32_b32 %0, -1, %0" : "=v"(l)); return l; }
; __device__ __forceinline__ void attn_sample_item(const Params& p, int item, const int wv) {
;   const int lane = lane_fresh(), wid = wv, tid = wv * 64 + lane;
;   const int h = item & 3, b = item >> 2, tok = TP + b;
;   float* sc_l = (float*)g_shm;
;   float* red_l = sc_l + 256;
;   u16* Q = (u16*)((char*)p.out + OOFF_Q);
;   const float* Kc = p.in[3] + ((size_t)b * 256 * 4 + h) * 128;
;   const float* Vc = p.in[4] + ((size_t)b * 256 * 4 + h) * 128;
;   const int vdch = tid & 31, vmg = tid >> 5;
;   f32x4 vreg[16];
; #pragma unroll
;   for (int i = 0; i < 16; ++i) vreg[i] = *(const f32x4*)(Vc + (size_t)(vmg * 16 + i) * 512 + vdch * 4);
;   __syncthreads();
;   {
;     const int dch = lane & 15, ksub = lane >> 4;
;     u32x4 qw = *(const u32x4*)(Q + (size_t)tok * 512 + h * 128 + dch * 8);
;     float q[8] = {bflo(qw.x), bfhi(qw.x), bflo(qw.y), bfhi(qw.y), bflo(qw.z), bfhi(qw.z), bflo(qw.w), bfhi(qw.w)};
; #pragma unroll
;     for (int it = 0; it < 8; ++it) {
;       const int mm = wid * 32 + it * 4 + ksub;
;       f32x4 k0 = *(const f32x4*)(Kc + (size_t)mm * 512 + dch * 8), k1 = *(const f32x4*)(Kc + (size_t)mm * 512 + dch * 8 + 4);
;       float d = q[0] * k0[0] + q[1] * k0[1] + q[2] * k0[2] + q[3] * k0[3] + q[4] * k1[0] + q[5] * k1[1] + q[6] * k1[2] + q[7] * k1[3];
.LBB0_464:
	s_ashr_i32 s0, s19, 2
	s_ashr_i32 s1, s0, 31
	s_and_b32 s22, s15, 0x180
	v_readlane_b32 s64, v251, 6
	s_lshl_b64 s[10:11], s[0:1], 19
	s_lshl_b32 s1, s22, 2
	v_readlane_b32 s72, v251, 14
	v_readlane_b32 s73, v251, 15
	s_or_b32 s1, s10, s1
	s_mov_b64 s[44:45], s[72:73]
	v_readlane_b32 s70, v251, 12
	v_readlane_b32 s71, v251, 13
	s_add_u32 s20, s44, s1
	v_mbcnt_lo_u32_b32 v72, -1, 0
	v_mbcnt_hi_u32_b32 v72, -1, v72
	s_mov_b64 s[42:43], s[70:71]
	v_add_u32_e32 v66, s82, v72
	s_addc_u32 s21, s45, s11
	s_addk_i32 s0, 0x4000
	v_and_b32_e32 v0, 31, v72
	v_ashrrev_i32_e32 v67, 5, v66
	s_add_u32 s10, s42, s1
	v_lshlrev_b32_e32 v56, 4, v67
	v_lshlrev_b32_e32 v64, 4, v0
	s_addc_u32 s11, s43, s11
	s_ashr_i32 s1, s0, 31
	v_lshl_add_u64 v[58:59], s[20:21], 0, v[64:65]
	v_ashrrev_i32_e32 v57, 31, v56
	s_lshl_b64 s[20:21], s[0:1], 10
	s_waitcnt lgkmcnt(0)
	v_lshlrev_b64 v[0:1], 11, v[56:57]
	v_or_b32_e32 v2, 1, v56
	v_or_b32_e32 v8, 2, v56
	v_or_b32_e32 v10, 3, v56
	v_or_b32_e32 v16, 4, v56
	v_or_b32_e32 v18, 5, v56
	v_or_b32_e32 v24, 6, v56
	v_or_b32_e32 v26, 7, v56
	v_or_b32_e32 v32, 8, v56
	v_or_b32_e32 v34, 9, v56
	v_or_b32_e32 v40, 10, v56
	v_or_b32_e32 v42, 11, v56
	v_or_b32_e32 v48, 12, v56
	v_or_b32_e32 v50, 13, v56
	v_or_b32_e32 v60, 14, v56
	v_or_b32_e32 v56, 15, v56
	s_add_u32 s23, s7, s20
	v_ashrrev_i32_e32 v3, 31, v2
	v_ashrrev_i32_e32 v9, 31, v8
	v_ashrrev_i32_e32 v11, 31, v10
	v_ashrrev_i32_e32 v17, 31, v16
	v_ashrrev_i32_e32 v19, 31, v18
	v_ashrrev_i32_e32 v25, 31, v24
	v_ashrrev_i32_e32 v27, 31, v26
	v_ashrrev_i32_e32 v33, 31, v32
	v_ashrrev_i32_e32 v35, 31, v34
	v_ashrrev_i32_e32 v41, 31, v40
	v_ashrrev_i32_e32 v43, 31, v42
	v_ashrrev_i32_e32 v49, 31, v48
	v_ashrrev_i32_e32 v51, 31, v50
	v_ashrrev_i32_e32 v61, 31, v60
	v_ashrrev_i32_e32 v57, 31, v56
	s_addc_u32 s21, s12, s21
	s_lshl_b32 s20, s22, 1
	v_lshlrev_b64 v[2:3], 11, v[2:3]
	v_lshlrev_b64 v[8:9], 11, v[8:9]
	v_lshlrev_b64 v[10:11], 11, v[10:11]
	v_lshlrev_b64 v[16:17], 11, v[16:17]
	v_lshlrev_b64 v[18:19], 11, v[18:19]
	v_lshlrev_b64 v[24:25], 11, v[24:25]
	v_lshlrev_b64 v[26:27], 11, v[26:27]
	v_lshlrev_b64 v[32:33], 11, v[32:33]
	v_lshlrev_b64 v[34:35], 11, v[34:35]
	v_lshlrev_b64 v[40:41], 11, v[40:41]
	v_lshlrev_b64 v[42:43], 11, v[42:43]
	v_lshlrev_b64 v[48:49], 11, v[48:49]
	v_lshlrev_b64 v[50:51], 11, v[50:51]
	v_lshlrev_b64 v[60:61], 11, v[60:61]
	v_lshlrev_b64 v[56:57], 11, v[56:57]
	v_and_b32_e32 v92, 15, v72
	v_ashrrev_i32_e32 v68, 4, v72
	s_add_u32 s22, s23, s20
	v_lshl_add_u64 v[0:1], v[58:59], 0, v[0:1]
	v_lshl_add_u64 v[2:3], v[58:59], 0, v[2:3]
	v_lshl_add_u64 v[8:9], v[58:59], 0, v[8:9]
	v_lshl_add_u64 v[10:11], v[58:59], 0, v[10:11]
	v_lshl_add_u64 v[16:17], v[58:59], 0, v[16:17]
	v_lshl_add_u64 v[18:19], v[58:59], 0, v[18:19]
	v_lshl_add_u64 v[24:25], v[58:59], 0, v[24:25]
	v_lshl_add_u64 v[26:27], v[58:59], 0, v[26:27]
	v_lshl_add_u64 v[32:33], v[58:59], 0, v[32:33]
	v_lshl_add_u64 v[34:35], v[58:59], 0, v[34:35]
	v_lshl_add_u64 v[40:41], v[58:59], 0, v[40:41]
	v_lshl_add_u64 v[42:43], v[58:59], 0, v[42:43]
	v_lshl_add_u64 v[48:49], v[58:59], 0, v[48:49]
	v_lshl_add_u64 v[50:51], v[58:59], 0, v[50:51]
	v_lshl_add_u64 v[60:61], v[58:59], 0, v[60:61]
	v_lshl_add_u64 v[56:57], v[58:59], 0, v[56:57]
	s_addc_u32 s23, s21, 0
	v_lshlrev_b32_e32 v69, 4, v92
	v_add_u32_e32 v70, s5, v68
	global_load_dwordx4 v[4:7], v[0:1], off
	s_nop 0
	global_load_dwordx4 v[0:3], v[2:3], off
	s_nop 0
	global_load_dwordx4 v[12:15], v[8:9], off
	s_nop 0
	global_load_dwordx4 v[8:11], v[10:11], off
	s_nop 0
	global_load_dwordx4 v[20:23], v[16:17], off
	s_nop 0
	global_load_dwordx4 v[16:19], v[18:19], off
	s_nop 0
	global_load_dwordx4 v[28:31], v[24:25], off
	s_nop 0
	global_load_dwordx4 v[24:27], v[26:27], off
	s_nop 0
	global_load_dwordx4 v[36:39], v[32:33], off
	s_nop 0
	global_load_dwordx4 v[32:35], v[34:35], off
	s_nop 0
	global_load_dwordx4 v[44:47], v[40:41], off
	s_nop 0
	global_load_dwordx4 v[40:43], v[42:43], off
	s_nop 0
	global_load_dwordx4 v[52:55], v[48:49], off
	s_nop 0
	global_load_dwordx4 v[48:51], v[50:51], off
	s_nop 0
	global_load_dwordx4 v[60:63], v[60:61], off
	s_nop 0
	global_load_dwordx4 v[56:59], v[56:57], off
	s_barrier
	global_load_dwordx4 v[80:83], v69, s[22:23]
	v_lshlrev_b32_e32 v68, 5, v92
	v_mov_b32_e32 v69, v65
	v_ashrrev_i32_e32 v71, 31, v70
	v_lshl_add_u64 v[68:69], s[10:11], 0, v[68:69]
	v_lshlrev_b64 v[74:75], 11, v[70:71]
	v_lshl_add_u64 v[74:75], v[68:69], 0, v[74:75]
	global_load_dwordx4 v[84:87], v[74:75], off
	global_load_dwordx4 v[88:91], v[74:75], off offset:16
	v_mov_b32_e32 v221, 0
	v_mov_b32_e32 v220, 0x2000
	v_lshl_add_u64 v[222:223], v[220:221], 0, v[74:75]
	global_load_dwordx4 v[164:167], v[222:223], off
	global_load_dwordx4 v[168:171], v[222:223], off offset:16
	v_mov_b32_e32 v220, 0x4000
	v_lshl_add_u64 v[222:223], v[220:221], 0, v[74:75]
	global_load_dwordx4 v[172:175], v[222:223], off
	global_load_dwordx4 v[176:179], v[222:223], off offset:16
	v_mov_b32_e32 v220, 0x6000
	v_lshl_add_u64 v[222:223], v[220:221], 0, v[74:75]
	global_load_dwordx4 v[180:183], v[222:223], off
	global_load_dwordx4 v[184:187], v[222:223], off offset:16
	v_mov_b32_e32 v220, 0x8000
	v_lshl_add_u64 v[222:223], v[220:221], 0, v[74:75]
	global_load_dwordx4 v[188:191], v[222:223], off
	global_load_dwordx4 v[192:195], v[222:223], off offset:16
	v_mov_b32_e32 v220, 0xa000
	v_lshl_add_u64 v[222:223], v[220:221], 0, v[74:75]
	global_load_dwordx4 v[196:199], v[222:223], off
	global_load_dwordx4 v[200:203], v[222:223], off offset:16
	v_mov_b32_e32 v220, 0xc000
	v_lshl_add_u64 v[222:223], v[220:221], 0, v[74:75]
	global_load_dwordx4 v[204:207], v[222:223], off
	global_load_dwordx4 v[208:211], v[222:223], off offset:16
	v_mov_b32_e32 v220, 0xe000
	v_lshl_add_u64 v[222:223], v[220:221], 0, v[74:75]
	global_load_dwordx4 v[212:215], v[222:223], off
	global_load_dwordx4 v[216:219], v[222:223], off offset:16
	v_cmp_eq_u32_e32 vcc, 0, v92
	v_readlane_b32 s65, v251, 7
	v_readlane_b32 s66, v251, 8
	v_readlane_b32 s67, v251, 9
	v_readlane_b32 s68, v251, 10
	v_readlane_b32 s69, v251, 11
	v_readlane_b32 s74, v251, 16
	v_readlane_b32 s75, v251, 17
	v_readlane_b32 s76, v251, 18
	v_readlane_b32 s77, v251, 19
	v_readlane_b32 s78, v251, 20
	v_readlane_b32 s79, v251, 21
	s_waitcnt vmcnt(16)
; __device__ __forceinline__ float bflo(unsigned w) { return __uint_as_float(w << 16); }
; __device__ __forceinline__ float bfhi(unsigned w) { return __uint_as_float(w & 0xffff0000u); }
; __device__ __forceinline__ float shfl_xor_f(float v, int mask) { const int l = lane_fresh(); return __int_as_float(__builtin_amdgcn_ds_bpermute((l ^ mask) << 2, __float_as_int(v))); }
; __device__ __forceinline__ void attn_sample_item(const Params& p, int item, const int wv) {
;     ...
;     const int dch = lane & 15, ksub = lane >> 4;
;     u32x4 qw = *(const u32x4*)(Q + (size_t)tok * 512 + h * 128 + dch * 8);
;     float q[8] = {bflo(qw.x), bfhi(qw.x), bflo(qw.y), bfhi(qw.y), bflo(qw.z), bfhi(qw.z), bflo(qw.w), bfhi(qw.w)};
; #pragma unroll
;     for (int it = 0; it < 8; ++it) {
;       const int mm = wid * 32 + it * 4 + ksub;
;       f32x4 k0 = *(const f32x4*)(Kc + (size_t)mm * 512 + dch * 8), k1 = *(const f32x4*)(Kc + (size_t)mm * 512 + dch * 8 + 4);
;       float d = q[0] * k0[0] + q[1] * k0[1] + q[2] * k0[2] + q[3] * k0[3] + q[4] * k1[0] + q[5] * k1[1] + q[6] * k1[2] + q[7] * k1[3];
;       d += shfl_xor_f(d, 1); d += shfl_xor_f(d, 2); d += shfl_xor_f(d, 4); d += shfl_xor_f(d, 8);
;       if (dch == 0) sc_l[mm] = d * 0.08838834764831845f;
;     }
	v_and_b32_e32 v79, 0xffff0000, v80
	v_lshlrev_b32_e32 v71, 16, v80
	v_lshlrev_b32_e32 v73, 16, v81
	v_and_b32_e32 v74, 0xffff0000, v81
	v_lshlrev_b32_e32 v75, 16, v82
	v_and_b32_e32 v76, 0xffff0000, v82
	s_waitcnt vmcnt(15)
	v_mul_f32_e32 v80, v85, v79
	v_fmac_f32_e32 v80, v84, v71
	v_fmac_f32_e32 v80, v86, v73
	v_fmac_f32_e32 v80, v87, v74
	s_waitcnt vmcnt(14)
	v_fmac_f32_e32 v80, v88, v75
	v_lshlrev_b32_e32 v77, 16, v83
	v_fmac_f32_e32 v80, v89, v76
	v_mbcnt_lo_u32_b32 v81, -1, 0
	v_mbcnt_hi_u32_b32 v81, -1, v81
	v_and_b32_e32 v78, 0xffff0000, v83
	v_fmac_f32_e32 v80, v90, v77
	v_lshlrev_b32_e32 v81, 2, v81
	v_fmac_f32_e32 v80, v91, v78
	v_xor_b32_e32 v81, 4, v81
	ds_bpermute_b32 v81, v81, v80
	s_waitcnt lgkmcnt(0)
	v_add_f32_e32 v80, v80, v81
	v_mbcnt_lo_u32_b32 v81, -1, 0
	v_mbcnt_hi_u32_b32 v81, -1, v81
	s_nop 0
	v_lshlrev_b32_e32 v81, 2, v81
	v_xor_b32_e32 v81, 8, v81
	ds_bpermute_b32 v81, v81, v80
	s_waitcnt lgkmcnt(0)
	v_add_f32_e32 v80, v80, v81
	v_mbcnt_lo_u32_b32 v81, -1, 0
	v_mbcnt_hi_u32_b32 v81, -1, v81
	s_nop 0
	v_lshlrev_b32_e32 v81, 2, v81
	v_xor_b32_e32 v81, 16, v81
	ds_bpermute_b32 v81, v81, v80
	s_waitcnt lgkmcnt(0)
	v_add_f32_e32 v81, v80, v81
	v_mbcnt_lo_u32_b32 v80, -1, 0
	v_mbcnt_hi_u32_b32 v80, -1, v80
	s_nop 0
	v_lshlrev_b32_e32 v80, 2, v80
	v_xor_b32_e32 v80, 32, v80
	ds_bpermute_b32 v82, v80, v81
	v_lshl_add_u32 v80, v70, 2, 16
	s_and_saveexec_b64 s[10:11], vcc
	s_cbranch_execz .LBB0_466
	s_waitcnt lgkmcnt(0)
	v_add_f32_e32 v81, v81, v82
	v_mul_f32_e32 v81, 0x3db504f3, v81
	ds_write_b32 v80, v81
.LBB0_466:
	s_or_b64 exec, exec, s[10:11]
	s_waitcnt lgkmcnt(0)
	v_add_u32_e32 v82, 4, v70
	v_ashrrev_i32_e32 v83, 31, v82
	v_lshlrev_b64 v[82:83], 11, v[82:83]
	v_lshl_add_u64 v[86:87], v[68:69], 0, v[82:83]
	s_nop 0
	v_mbcnt_lo_u32_b32 v81, -1, 0
	v_mbcnt_hi_u32_b32 v81, -1, v81
	s_waitcnt vmcnt(12)
	v_mul_f32_e32 v83, v165, v79
	v_fmac_f32_e32 v83, v164, v71
	v_fmac_f32_e32 v83, v166, v73
	v_fmac_f32_e32 v83, v167, v74
	v_fmac_f32_e32 v83, v168, v75
	v_fmac_f32_e32 v83, v169, v76
	v_lshlrev_b32_e32 v81, 2, v81
	v_fmac_f32_e32 v83, v170, v77
	v_xor_b32_e32 v81, 4, v81
	v_fmac_f32_e32 v83, v171, v78
	ds_bpermute_b32 v81, v81, v83
	v_mbcnt_lo_u32_b32 v82, -1, 0
	v_mbcnt_hi_u32_b32 v82, -1, v82
	s_waitcnt lgkmcnt(0)
	v_add_f32_e32 v81, v83, v81
	v_lshlrev_b32_e32 v82, 2, v82
	v_xor_b32_e32 v82, 8, v82
	ds_bpermute_b32 v82, v82, v81
	v_mbcnt_lo_u32_b32 v83, -1, 0
	v_mbcnt_hi_u32_b32 v83, -1, v83
	s_waitcnt lgkmcnt(0)
	v_add_f32_e32 v81, v81, v82
	v_lshlrev_b32_e32 v83, 2, v83
	v_xor_b32_e32 v83, 16, v83
	ds_bpermute_b32 v82, v83, v81
	v_mbcnt_lo_u32_b32 v83, -1, 0
	v_mbcnt_hi_u32_b32 v83, -1, v83
	s_waitcnt lgkmcnt(0)
	v_add_f32_e32 v81, v81, v82
	v_lshlrev_b32_e32 v83, 2, v83
	v_xor_b32_e32 v82, 32, v83
	ds_bpermute_b32 v82, v82, v81
	s_and_saveexec_b64 s[10:11], vcc
	s_cbranch_execz .LBB0_468
	s_waitcnt lgkmcnt(0)
	v_add_f32_e32 v81, v81, v82
	v_mul_f32_e32 v81, 0x3db504f3, v81
	ds_write_b32 v80, v81 offset:16
.LBB0_468:
	s_or_b64 exec, exec, s[10:11]
	s_waitcnt lgkmcnt(0)
	v_add_u32_e32 v82, 8, v70
	v_ashrrev_i32_e32 v83, 31, v82
	v_lshlrev_b64 v[82:83], 11, v[82:83]
	v_lshl_add_u64 v[86:87], v[68:69], 0, v[82:83]
	s_nop 0
	v_mbcnt_lo_u32_b32 v81, -1, 0
	v_mbcnt_hi_u32_b32 v81, -1, v81
	s_waitcnt vmcnt(10)
	v_mul_f32_e32 v83, v173, v79
	v_fmac_f32_e32 v83, v172, v71
	v_fmac_f32_e32 v83, v174, v73
	v_fmac_f32_e32 v83, v175, v74
	v_fmac_f32_e32 v83, v176, v75
	v_fmac_f32_e32 v83, v177, v76
	v_lshlrev_b32_e32 v81, 2, v81
	v_fmac_f32_e32 v83, v178, v77
	v_xor_b32_e32 v81, 4, v81
	v_fmac_f32_e32 v83, v179, v78
	ds_bpermute_b32 v81, v81, v83
	v_mbcnt_lo_u32_b32 v82, -1, 0
	v_mbcnt_hi_u32_b32 v82, -1, v82
	s_waitcnt lgkmcnt(0)
	v_add_f32_e32 v81, v83, v81
	v_lshlrev_b32_e32 v82, 2, v82
	v_xor_b32_e32 v82, 8, v82
	ds_bpermute_b32 v82, v82, v81
	v_mbcnt_lo_u32_b32 v83, -1, 0
	v_mbcnt_hi_u32_b32 v83, -1, v83
	s_waitcnt lgkmcnt(0)
	v_add_f32_e32 v81, v81, v82
	v_lshlrev_b32_e32 v83, 2, v83
	v_xor_b32_e32 v83, 16, v83
	ds_bpermute_b32 v82, v83, v81
	v_mbcnt_lo_u32_b32 v83, -1, 0
	v_mbcnt_hi_u32_b32 v83, -1, v83
	s_waitcnt lgkmcnt(0)
	v_add_f32_e32 v81, v81, v82
	v_lshlrev_b32_e32 v83, 2, v83
	v_xor_b32_e32 v82, 32, v83
	ds_bpermute_b32 v82, v82, v81
	s_and_saveexec_b64 s[10:11], vcc
	s_cbranch_execz .LBB0_470
	s_waitcnt lgkmcnt(0)
	v_add_f32_e32 v81, v81, v82
	v_mul_f32_e32 v81, 0x3db504f3, v81
	ds_write_b32 v80, v81 offset:32
.LBB0_470:
	s_or_b64 exec, exec, s[10:11]
	s_waitcnt lgkmcnt(0)
	v_add_u32_e32 v82, 12, v70
	v_ashrrev_i32_e32 v83, 31, v82
	v_lshlrev_b64 v[82:83], 11, v[82:83]
	v_lshl_add_u64 v[86:87], v[68:69], 0, v[82:83]
	s_nop 0
	v_mbcnt_lo_u32_b32 v81, -1, 0
	v_mbcnt_hi_u32_b32 v81, -1, v81
	s_waitcnt vmcnt(8)
	v_mul_f32_e32 v83, v181, v79
	v_fmac_f32_e32 v83, v180, v71
	v_fmac_f32_e32 v83, v182, v73
	v_fmac_f32_e32 v83, v183, v74
	v_fmac_f32_e32 v83, v184, v75
	v_fmac_f32_e32 v83, v185, v76
	v_lshlrev_b32_e32 v81, 2, v81
	v_fmac_f32_e32 v83, v186, v77
	v_xor_b32_e32 v81, 4, v81
	v_fmac_f32_e32 v83, v187, v78
	ds_bpermute_b32 v81, v81, v83
	v_mbcnt_lo_u32_b32 v82, -1, 0
	v_mbcnt_hi_u32_b32 v82, -1, v82
	s_waitcnt lgkmcnt(0)
	v_add_f32_e32 v81, v83, v81
	v_lshlrev_b32_e32 v82, 2, v82
	v_xor_b32_e32 v82, 8, v82
	ds_bpermute_b32 v82, v82, v81
	v_mbcnt_lo_u32_b32 v83, -1, 0
	v_mbcnt_hi_u32_b32 v83, -1, v83
	s_waitcnt lgkmcnt(0)
	v_add_f32_e32 v81, v81, v82
	v_lshlrev_b32_e32 v83, 2, v83
	v_xor_b32_e32 v83, 16, v83
	ds_bpermute_b32 v82, v83, v81
	v_mbcnt_lo_u32_b32 v83, -1, 0
	v_mbcnt_hi_u32_b32 v83, -1, v83
	s_waitcnt lgkmcnt(0)
	v_add_f32_e32 v81, v81, v82
	v_lshlrev_b32_e32 v83, 2, v83
	v_xor_b32_e32 v82, 32, v83
	ds_bpermute_b32 v82, v82, v81
	s_and_saveexec_b64 s[10:11], vcc
	s_cbranch_execz .LBB0_472
	s_waitcnt lgkmcnt(0)
	v_add_f32_e32 v81, v81, v82
	v_mul_f32_e32 v81, 0x3db504f3, v81
	ds_write_b32 v80, v81 offset:48
; __device__ __forceinline__ float shfl_xor_f(float v, int mask) { const int l = lane_fresh(); return __int_as_float(__builtin_amdgcn_ds_bpermute((l ^ mask) << 2, __float_as_int(v))); }
; __device__ __forceinline__ void attn_sample_item(const Params& p, int item, const int wv) {
;     ...
;     for (int it = 0; it < 8; ++it) {
;       const int mm = wid * 32 + it * 4 + ksub;
;       f32x4 k0 = *(const f32x4*)(Kc + (size_t)mm * 512 + dch * 8), k1 = *(const f32x4*)(Kc + (size_t)mm * 512 + dch * 8 + 4);
;       float d = q[0] * k0[0] + q[1] * k0[1] + q[2] * k0[2] + q[3] * k0[3] + q[4] * k1[0] + q[5] * k1[1] + q[6] * k1[2] + q[7] * k1[3];
;       d += shfl_xor_f(d, 1); d += shfl_xor_f(d, 2); d += shfl_xor_f(d, 4); d += shfl_xor_f(d, 8);
;       if (dch == 0) sc_l[mm] = d * 0.08838834764831845f;
;     }
.LBB0_472:
	s_or_b64 exec, exec, s[10:11]
	s_waitcnt lgkmcnt(0)
	v_add_u32_e32 v82, 16, v70
	v_ashrrev_i32_e32 v83, 31, v82
	v_lshlrev_b64 v[82:83], 11, v[82:83]
	v_lshl_add_u64 v[86:87], v[68:69], 0, v[82:83]
	s_nop 0
	v_mbcnt_lo_u32_b32 v81, -1, 0
	v_mbcnt_hi_u32_b32 v81, -1, v81
	s_waitcnt vmcnt(6)
	v_mul_f32_e32 v83, v189, v79
	v_fmac_f32_e32 v83, v188, v71
	v_fmac_f32_e32 v83, v190, v73
	v_fmac_f32_e32 v83, v191, v74
	v_fmac_f32_e32 v83, v192, v75
	v_fmac_f32_e32 v83, v193, v76
	v_lshlrev_b32_e32 v81, 2, v81
	v_fmac_f32_e32 v83, v194, v77
	v_xor_b32_e32 v81, 4, v81
	v_fmac_f32_e32 v83, v195, v78
	ds_bpermute_b32 v81, v81, v83
	v_mbcnt_lo_u32_b32 v82, -1, 0
	v_mbcnt_hi_u32_b32 v82, -1, v82
	s_waitcnt lgkmcnt(0)
	v_add_f32_e32 v81, v83, v81
	v_lshlrev_b32_e32 v82, 2, v82
	v_xor_b32_e32 v82, 8, v82
	ds_bpermute_b32 v82, v82, v81
	v_mbcnt_lo_u32_b32 v83, -1, 0
	v_mbcnt_hi_u32_b32 v83, -1, v83
	s_waitcnt lgkmcnt(0)
	v_add_f32_e32 v81, v81, v82
	v_lshlrev_b32_e32 v83, 2, v83
	v_xor_b32_e32 v83, 16, v83
	ds_bpermute_b32 v82, v83, v81
	v_mbcnt_lo_u32_b32 v83, -1, 0
	v_mbcnt_hi_u32_b32 v83, -1, v83
	s_waitcnt lgkmcnt(0)
	v_add_f32_e32 v81, v81, v82
	v_lshlrev_b32_e32 v83, 2, v83
	v_xor_b32_e32 v82, 32, v83
	ds_bpermute_b32 v82, v82, v81
	s_and_saveexec_b64 s[10:11], vcc
	s_cbranch_execz .LBB0_474
	s_waitcnt lgkmcnt(0)
	v_add_f32_e32 v81, v81, v82
	v_mul_f32_e32 v81, 0x3db504f3, v81
	ds_write_b32 v80, v81 offset:64
.LBB0_474:
	s_or_b64 exec, exec, s[10:11]
	s_waitcnt lgkmcnt(0)
	v_add_u32_e32 v82, 20, v70
	v_ashrrev_i32_e32 v83, 31, v82
	v_lshlrev_b64 v[82:83], 11, v[82:83]
	v_lshl_add_u64 v[86:87], v[68:69], 0, v[82:83]
	s_nop 0
	v_mbcnt_lo_u32_b32 v81, -1, 0
	v_mbcnt_hi_u32_b32 v81, -1, v81
	s_waitcnt vmcnt(4)
	v_mul_f32_e32 v83, v197, v79
	v_fmac_f32_e32 v83, v196, v71
	v_fmac_f32_e32 v83, v198, v73
	v_fmac_f32_e32 v83, v199, v74
	v_fmac_f32_e32 v83, v200, v75
	v_fmac_f32_e32 v83, v201, v76
	v_lshlrev_b32_e32 v81, 2, v81
	v_fmac_f32_e32 v83, v202, v77
	v_xor_b32_e32 v81, 4, v81
	v_fmac_f32_e32 v83, v203, v78
	ds_bpermute_b32 v81, v81, v83
	v_mbcnt_lo_u32_b32 v82, -1, 0
	v_mbcnt_hi_u32_b32 v82, -1, v82
	s_waitcnt lgkmcnt(0)
	v_add_f32_e32 v81, v83, v81
	v_lshlrev_b32_e32 v82, 2, v82
	v_xor_b32_e32 v82, 8, v82
	ds_bpermute_b32 v82, v82, v81
	v_mbcnt_lo_u32_b32 v83, -1, 0
	v_mbcnt_hi_u32_b32 v83, -1, v83
	s_waitcnt lgkmcnt(0)
	v_add_f32_e32 v81, v81, v82
	v_lshlrev_b32_e32 v83, 2, v83
	v_xor_b32_e32 v83, 16, v83
	ds_bpermute_b32 v82, v83, v81
	v_mbcnt_lo_u32_b32 v83, -1, 0
	v_mbcnt_hi_u32_b32 v83, -1, v83
	s_waitcnt lgkmcnt(0)
	v_add_f32_e32 v81, v81, v82
	v_lshlrev_b32_e32 v83, 2, v83
	v_xor_b32_e32 v82, 32, v83
	ds_bpermute_b32 v82, v82, v81
	s_and_saveexec_b64 s[10:11], vcc
	s_cbranch_execz .LBB0_476
	s_waitcnt lgkmcnt(0)
	v_add_f32_e32 v81, v81, v82
	v_mul_f32_e32 v81, 0x3db504f3, v81
	ds_write_b32 v80, v81 offset:80
.LBB0_476:
	s_or_b64 exec, exec, s[10:11]
	s_waitcnt lgkmcnt(0)
	v_add_u32_e32 v82, 24, v70
	v_ashrrev_i32_e32 v83, 31, v82
	v_lshlrev_b64 v[82:83], 11, v[82:83]
	v_lshl_add_u64 v[86:87], v[68:69], 0, v[82:83]
	s_nop 0
	v_mbcnt_lo_u32_b32 v81, -1, 0
	v_mbcnt_hi_u32_b32 v81, -1, v81
	s_waitcnt vmcnt(2)
	v_mul_f32_e32 v83, v205, v79
	v_fmac_f32_e32 v83, v204, v71
	v_fmac_f32_e32 v83, v206, v73
	v_fmac_f32_e32 v83, v207, v74
	v_fmac_f32_e32 v83, v208, v75
	v_fmac_f32_e32 v83, v209, v76
	v_lshlrev_b32_e32 v81, 2, v81
	v_fmac_f32_e32 v83, v210, v77
	v_xor_b32_e32 v81, 4, v81
	v_fmac_f32_e32 v83, v211, v78
	ds_bpermute_b32 v81, v81, v83
	v_mbcnt_lo_u32_b32 v82, -1, 0
	v_mbcnt_hi_u32_b32 v82, -1, v82
	s_waitcnt lgkmcnt(0)
	v_add_f32_e32 v81, v83, v81
	v_lshlrev_b32_e32 v82, 2, v82
	v_xor_b32_e32 v82, 8, v82
	ds_bpermute_b32 v82, v82, v81
	v_mbcnt_lo_u32_b32 v83, -1, 0
	v_mbcnt_hi_u32_b32 v83, -1, v83
	s_waitcnt lgkmcnt(0)
	v_add_f32_e32 v81, v81, v82
	v_lshlrev_b32_e32 v83, 2, v83
	v_xor_b32_e32 v83, 16, v83
	ds_bpermute_b32 v82, v83, v81
	v_mbcnt_lo_u32_b32 v83, -1, 0
	v_mbcnt_hi_u32_b32 v83, -1, v83
	s_waitcnt lgkmcnt(0)
	v_add_f32_e32 v81, v81, v82
	v_lshlrev_b32_e32 v83, 2, v83
	v_xor_b32_e32 v82, 32, v83
	ds_bpermute_b32 v82, v82, v81
	s_and_saveexec_b64 s[10:11], vcc
	s_cbranch_execz .LBB0_478
	s_waitcnt lgkmcnt(0)
	v_add_f32_e32 v81, v81, v82
	v_mul_f32_e32 v81, 0x3db504f3, v81
	ds_write_b32 v80, v81 offset:96
.LBB0_478:
	s_or_b64 exec, exec, s[10:11]
	s_waitcnt lgkmcnt(0)
	v_add_u32_e32 v82, 28, v70
	v_ashrrev_i32_e32 v83, 31, v82
	v_lshlrev_b64 v[82:83], 11, v[82:83]
	v_lshl_add_u64 v[68:69], v[68:69], 0, v[82:83]
	v_mbcnt_lo_u32_b32 v68, -1, 0
	v_mbcnt_hi_u32_b32 v68, -1, v68
	v_mbcnt_lo_u32_b32 v70, -1, 0
	v_mbcnt_hi_u32_b32 v70, -1, v70
	s_waitcnt vmcnt(0)
	v_mul_f32_e32 v69, v213, v79
	v_fmac_f32_e32 v69, v212, v71
	v_fmac_f32_e32 v69, v214, v73
	v_fmac_f32_e32 v69, v215, v74
	v_fmac_f32_e32 v69, v216, v75
	v_fmac_f32_e32 v69, v217, v76
	v_lshlrev_b32_e32 v68, 2, v68
	v_fmac_f32_e32 v69, v218, v77
	v_xor_b32_e32 v68, 4, v68
	v_fmac_f32_e32 v69, v219, v78
	ds_bpermute_b32 v68, v68, v69
	v_lshlrev_b32_e32 v70, 2, v70
	v_xor_b32_e32 v70, 8, v70
	s_waitcnt lgkmcnt(0)
	v_add_f32_e32 v68, v69, v68
	ds_bpermute_b32 v69, v70, v68
	v_mbcnt_lo_u32_b32 v70, -1, 0
	v_mbcnt_hi_u32_b32 v70, -1, v70
	s_waitcnt lgkmcnt(0)
	v_add_f32_e32 v68, v68, v69
	v_lshlrev_b32_e32 v70, 2, v70
	v_xor_b32_e32 v70, 16, v70
	ds_bpermute_b32 v69, v70, v68
	v_mbcnt_lo_u32_b32 v70, -1, 0
	v_mbcnt_hi_u32_b32 v70, -1, v70
	s_waitcnt lgkmcnt(0)
	v_add_f32_e32 v68, v68, v69
	v_lshlrev_b32_e32 v70, 2, v70
	v_xor_b32_e32 v69, 32, v70
	ds_bpermute_b32 v69, v69, v68
	s_and_saveexec_b64 s[10:11], vcc
	s_cbranch_execz .LBB0_480
	s_waitcnt lgkmcnt(0)
	v_add_f32_e32 v68, v68, v69
	v_mul_f32_e32 v68, 0x3db504f3, v68
	ds_write_b32 v80, v68 offset:112

; __device__ __forceinline__ float bflo(unsigned w) { return __uint_as_float(w << 16); }
; __device__ __forceinline__ float bfhi(unsigned w) { return __uint_as_float(w & 0xffff0000u); }
; __device__ __forceinline__ int lane_fresh() { int l; asm volatile("v_mbcnt_lo_u32_b32 %0, -1, 0\n\tv_mbcnt_hi_u32_b32 %0, -1, %0" : "=v"(l)); return l; }
; __device__ __forceinline__ void attn_sample_item(const Params& p, int item, const int wv) {
;   const int lane = lane_fresh(), wid = wv, tid = wv * 64 + lane;
;   const int h = item & 3, b = item >> 2, tok = TP + b;
;   float* sc_l = (float*)g_shm;
;   float* red_l = sc_l + 256;
;   u16* Q = (u16*)((char*)p.out + OOFF_Q);
;   const float* Kc = p.in[3] + ((size_t)b * 256 * 4 + h) * 128;
;   const float* Vc = p.in[4] + ((size_t)b * 256 * 4 + h) * 128;
;   const int vdch = tid & 31, vmg = tid >> 5;
;   f32x4 vreg[16];
; #pragma unroll
;   for (int i = 0; i < 16; ++i) vreg[i] = *(const f32x4*)(Vc + (size_t)(vmg * 16 + i) * 512 + vdch * 4);
;   __syncthreads();
;   {
;     const int dch = lane & 15, ksub = lane >> 4;
;     u32x4 qw = *(const u32x4*)(Q + (size_t)tok * 512 + h * 128 + dch * 8);
;     float q[8] = {bflo(qw.x), bfhi(qw.x), bflo(qw.y), bfhi(qw.y), bflo(qw.z), bfhi(qw.z), bflo(qw.w), bfhi(qw.w)};
; #pragma unroll
;     for (int it = 0; it < 8; ++it) {
;       const int mm = wid * 32 + it * 4 + ksub;
;       f32x4 k0 = *(const f32x4*)(Kc + (size_t)mm * 512 + dch * 8), k1 = *(const f32x4*)(Kc + (size_t)mm * 512 + dch * 8 + 4);
;       float d = q[0] * k0[0] + q[1] * k0[1] + q[2] * k0[2] + q[3] * k0[3] + q[4] * k1[0] + q[5] * k1[1] + q[6] * k1[2] + q[7] * k1[3];
.LBB0_490:
	s_lshr_b32 s0, s18, 2
	s_and_b32 s19, s14, 0x180
	v_readlane_b32 s64, v251, 6
	s_lshl_b32 s20, s19, 2
	s_lshl_b64 s[8:9], s[0:1], 19
	v_readlane_b32 s72, v251, 14
	v_readlane_b32 s73, v251, 15
	s_or_b32 s8, s8, s20
	s_mov_b64 s[44:45], s[72:73]
	v_mbcnt_lo_u32_b32 v72, -1, 0
	v_mbcnt_hi_u32_b32 v72, -1, v72
	v_readlane_b32 s70, v251, 12
	v_add_u32_e32 v66, s82, v72
	v_readlane_b32 s71, v251, 13
	s_add_u32 s20, s44, s8
	s_mov_b64 s[42:43], s[70:71]
	s_addc_u32 s21, s45, s9
	v_and_b32_e32 v0, 31, v72
	v_ashrrev_i32_e32 v67, 5, v66
	s_addk_i32 s0, 0x4000
	v_lshlrev_b32_e32 v56, 4, v67
	v_lshlrev_b32_e32 v64, 4, v0
	s_add_u32 s8, s42, s8
	v_lshl_add_u64 v[58:59], s[20:21], 0, v[64:65]
	v_ashrrev_i32_e32 v57, 31, v56
	s_addc_u32 s9, s43, s9
	s_lshl_b64 s[20:21], s[0:1], 10
	s_waitcnt lgkmcnt(0)
	v_lshlrev_b64 v[0:1], 11, v[56:57]
	v_or_b32_e32 v2, 1, v56
	v_or_b32_e32 v8, 2, v56
	v_or_b32_e32 v10, 3, v56
	v_or_b32_e32 v16, 4, v56
	v_or_b32_e32 v18, 5, v56
	v_or_b32_e32 v24, 6, v56
	v_or_b32_e32 v26, 7, v56
	v_or_b32_e32 v32, 8, v56
	v_or_b32_e32 v34, 9, v56
	v_or_b32_e32 v40, 10, v56
	v_or_b32_e32 v42, 11, v56
	v_or_b32_e32 v48, 12, v56
	v_or_b32_e32 v50, 13, v56
	v_or_b32_e32 v60, 14, v56
	v_or_b32_e32 v56, 15, v56
	s_add_u32 s20, s10, s20
	v_ashrrev_i32_e32 v3, 31, v2
	v_ashrrev_i32_e32 v9, 31, v8
	v_ashrrev_i32_e32 v11, 31, v10
	v_ashrrev_i32_e32 v17, 31, v16
	v_ashrrev_i32_e32 v19, 31, v18
	v_ashrrev_i32_e32 v25, 31, v24
	v_ashrrev_i32_e32 v27, 31, v26
	v_ashrrev_i32_e32 v33, 31, v32
	v_ashrrev_i32_e32 v35, 31, v34
	v_ashrrev_i32_e32 v41, 31, v40
	v_ashrrev_i32_e32 v43, 31, v42
	v_ashrrev_i32_e32 v49, 31, v48
	v_ashrrev_i32_e32 v51, 31, v50
	v_ashrrev_i32_e32 v61, 31, v60
	v_ashrrev_i32_e32 v57, 31, v56
	s_addc_u32 s21, s11, s21
	s_lshl_b32 s19, s19, 1
	v_lshlrev_b64 v[2:3], 11, v[2:3]
	v_lshlrev_b64 v[8:9], 11, v[8:9]
	v_lshlrev_b64 v[10:11], 11, v[10:11]
	v_lshlrev_b64 v[16:17], 11, v[16:17]
	v_lshlrev_b64 v[18:19], 11, v[18:19]
	v_lshlrev_b64 v[24:25], 11, v[24:25]
	v_lshlrev_b64 v[26:27], 11, v[26:27]
	v_lshlrev_b64 v[32:33], 11, v[32:33]
	v_lshlrev_b64 v[34:35], 11, v[34:35]
	v_lshlrev_b64 v[40:41], 11, v[40:41]
	v_lshlrev_b64 v[42:43], 11, v[42:43]
	v_lshlrev_b64 v[48:49], 11, v[48:49]
	v_lshlrev_b64 v[50:51], 11, v[50:51]
	v_lshlrev_b64 v[60:61], 11, v[60:61]
	v_lshlrev_b64 v[56:57], 11, v[56:57]
	v_and_b32_e32 v92, 15, v72
	v_ashrrev_i32_e32 v68, 4, v72
	s_add_u32 s20, s20, s19
	v_lshl_add_u64 v[0:1], v[58:59], 0, v[0:1]
	v_lshl_add_u64 v[2:3], v[58:59], 0, v[2:3]
	v_lshl_add_u64 v[8:9], v[58:59], 0, v[8:9]
	v_lshl_add_u64 v[10:11], v[58:59], 0, v[10:11]
	v_lshl_add_u64 v[16:17], v[58:59], 0, v[16:17]
	v_lshl_add_u64 v[18:19], v[58:59], 0, v[18:19]
	v_lshl_add_u64 v[24:25], v[58:59], 0, v[24:25]
	v_lshl_add_u64 v[26:27], v[58:59], 0, v[26:27]
	v_lshl_add_u64 v[32:33], v[58:59], 0, v[32:33]
	v_lshl_add_u64 v[34:35], v[58:59], 0, v[34:35]
	v_lshl_add_u64 v[40:41], v[58:59], 0, v[40:41]
	v_lshl_add_u64 v[42:43], v[58:59], 0, v[42:43]
	v_lshl_add_u64 v[48:49], v[58:59], 0, v[48:49]
	v_lshl_add_u64 v[50:51], v[58:59], 0, v[50:51]
	v_lshl_add_u64 v[60:61], v[58:59], 0, v[60:61]
	v_lshl_add_u64 v[56:57], v[58:59], 0, v[56:57]
	s_addc_u32 s21, s21, 0
	v_lshlrev_b32_e32 v69, 4, v92
	v_add_u32_e32 v70, s5, v68
	global_load_dwordx4 v[4:7], v[0:1], off
	s_nop 0
	global_load_dwordx4 v[0:3], v[2:3], off
	s_nop 0
	global_load_dwordx4 v[12:15], v[8:9], off
	s_nop 0
	global_load_dwordx4 v[8:11], v[10:11], off
	s_nop 0
	global_load_dwordx4 v[20:23], v[16:17], off
	s_nop 0
	global_load_dwordx4 v[16:19], v[18:19], off
	s_nop 0
	global_load_dwordx4 v[28:31], v[24:25], off
	s_nop 0
	global_load_dwordx4 v[24:27], v[26:27], off
	s_nop 0
	global_load_dwordx4 v[36:39], v[32:33], off
	s_nop 0
	global_load_dwordx4 v[32:35], v[34:35], off
	s_nop 0
	global_load_dwordx4 v[44:47], v[40:41], off
	s_nop 0
	global_load_dwordx4 v[40:43], v[42:43], off
	s_nop 0
	global_load_dwordx4 v[52:55], v[48:49], off
	s_nop 0
	global_load_dwordx4 v[48:51], v[50:51], off
	s_nop 0
	global_load_dwordx4 v[60:63], v[60:61], off
	s_nop 0
	global_load_dwordx4 v[56:59], v[56:57], off
	s_barrier
	global_load_dwordx4 v[80:83], v69, s[20:21]
	v_lshlrev_b32_e32 v68, 5, v92
	v_mov_b32_e32 v69, v65
	v_ashrrev_i32_e32 v71, 31, v70
	v_lshl_add_u64 v[68:69], s[8:9], 0, v[68:69]
	v_lshlrev_b64 v[74:75], 11, v[70:71]
	v_lshl_add_u64 v[74:75], v[68:69], 0, v[74:75]
	global_load_dwordx4 v[84:87], v[74:75], off
	global_load_dwordx4 v[88:91], v[74:75], off offset:16
	v_mov_b32_e32 v221, 0
	v_mov_b32_e32 v220, 0x2000
	v_lshl_add_u64 v[222:223], v[220:221], 0, v[74:75]
	global_load_dwordx4 v[164:167], v[222:223], off
	global_load_dwordx4 v[168:171], v[222:223], off offset:16
	v_mov_b32_e32 v220, 0x4000
	v_lshl_add_u64 v[222:223], v[220:221], 0, v[74:75]
	global_load_dwordx4 v[172:175], v[222:223], off
	global_load_dwordx4 v[176:179], v[222:223], off offset:16
	v_mov_b32_e32 v220, 0x6000
	v_lshl_add_u64 v[222:223], v[220:221], 0, v[74:75]
	global_load_dwordx4 v[180:183], v[222:223], off
	global_load_dwordx4 v[184:187], v[222:223], off offset:16
	v_mov_b32_e32 v220, 0x8000
	v_lshl_add_u64 v[222:223], v[220:221], 0, v[74:75]
	global_load_dwordx4 v[188:191], v[222:223], off
	global_load_dwordx4 v[192:195], v[222:223], off offset:16
	v_mov_b32_e32 v220, 0xa000
	v_lshl_add_u64 v[222:223], v[220:221], 0, v[74:75]
	global_load_dwordx4 v[196:199], v[222:223], off
	global_load_dwordx4 v[200:203], v[222:223], off offset:16
	v_mov_b32_e32 v220, 0xc000
	v_lshl_add_u64 v[222:223], v[220:221], 0, v[74:75]
	global_load_dwordx4 v[204:207], v[222:223], off
	global_load_dwordx4 v[208:211], v[222:223], off offset:16
	v_mov_b32_e32 v220, 0xe000
	v_lshl_add_u64 v[222:223], v[220:221], 0, v[74:75]
	global_load_dwordx4 v[212:215], v[222:223], off
	global_load_dwordx4 v[216:219], v[222:223], off offset:16
	v_cmp_eq_u32_e32 vcc, 0, v92
	v_readlane_b32 s65, v251, 7
	v_readlane_b32 s66, v251, 8
	v_readlane_b32 s67, v251, 9
	v_readlane_b32 s68, v251, 10
	v_readlane_b32 s69, v251, 11
	v_readlane_b32 s74, v251, 16
	v_readlane_b32 s75, v251, 17
	v_readlane_b32 s76, v251, 18
	v_readlane_b32 s77, v251, 19
	v_readlane_b32 s78, v251, 20
	v_readlane_b32 s79, v251, 21
	s_waitcnt vmcnt(16)
; __device__ __forceinline__ float bflo(unsigned w) { return __uint_as_float(w << 16); }
; __device__ __forceinline__ float bfhi(unsigned w) { return __uint_as_float(w & 0xffff0000u); }
; __device__ __forceinline__ float shfl_xor_f(float v, int mask) { const int l = lane_fresh(); return __int_as_float(__builtin_amdgcn_ds_bpermute((l ^ mask) << 2, __float_as_int(v))); }
; __device__ __forceinline__ void attn_sample_item(const Params& p, int item, const int wv) {
;     ...
;     const int dch = lane & 15, ksub = lane >> 4;
;     u32x4 qw = *(const u32x4*)(Q + (size_t)tok * 512 + h * 128 + dch * 8);
;     float q[8] = {bflo(qw.x), bfhi(qw.x), bflo(qw.y), bfhi(qw.y), bflo(qw.z), bfhi(qw.z), bflo(qw.w), bfhi(qw.w)};
; #pragma unroll
;     for (int it = 0; it < 8; ++it) {
;       const int mm = wid * 32 + it * 4 + ksub;
;       f32x4 k0 = *(const f32x4*)(Kc + (size_t)mm * 512 + dch * 8), k1 = *(const f32x4*)(Kc + (size_t)mm * 512 + dch * 8 + 4);
;       float d = q[0] * k0[0] + q[1] * k0[1] + q[2] * k0[2] + q[3] * k0[3] + q[4] * k1[0] + q[5] * k1[1] + q[6] * k1[2] + q[7] * k1[3];
;       d += shfl_xor_f(d, 1); d += shfl_xor_f(d, 2); d += shfl_xor_f(d, 4); d += shfl_xor_f(d, 8);
;       if (dch == 0) sc_l[mm] = d * 0.08838834764831845f;
;     }
	v_and_b32_e32 v79, 0xffff0000, v80
	v_lshlrev_b32_e32 v71, 16, v80
	v_lshlrev_b32_e32 v73, 16, v81
	v_and_b32_e32 v74, 0xffff0000, v81
	v_lshlrev_b32_e32 v75, 16, v82
	v_and_b32_e32 v76, 0xffff0000, v82
	s_waitcnt vmcnt(15)
	v_mul_f32_e32 v80, v85, v79
	v_fmac_f32_e32 v80, v84, v71
	v_fmac_f32_e32 v80, v86, v73
	v_fmac_f32_e32 v80, v87, v74
	s_waitcnt vmcnt(14)
	v_fmac_f32_e32 v80, v88, v75
	v_lshlrev_b32_e32 v77, 16, v83
	v_fmac_f32_e32 v80, v89, v76
	v_mbcnt_lo_u32_b32 v81, -1, 0
	v_mbcnt_hi_u32_b32 v81, -1, v81
	v_and_b32_e32 v78, 0xffff0000, v83
	v_fmac_f32_e32 v80, v90, v77
	v_lshlrev_b32_e32 v81, 2, v81
	v_fmac_f32_e32 v80, v91, v78
	v_xor_b32_e32 v81, 4, v81
	ds_bpermute_b32 v81, v81, v80
	s_waitcnt lgkmcnt(0)
	v_add_f32_e32 v80, v80, v81
	v_mbcnt_lo_u32_b32 v81, -1, 0
	v_mbcnt_hi_u32_b32 v81, -1, v81
	s_nop 0
	v_lshlrev_b32_e32 v81, 2, v81
	v_xor_b32_e32 v81, 8, v81
	ds_bpermute_b32 v81, v81, v80
	s_waitcnt lgkmcnt(0)
	v_add_f32_e32 v80, v80, v81
	v_mbcnt_lo_u32_b32 v81, -1, 0
	v_mbcnt_hi_u32_b32 v81, -1, v81
	s_nop 0
	v_lshlrev_b32_e32 v81, 2, v81
	v_xor_b32_e32 v81, 16, v81
	ds_bpermute_b32 v81, v81, v80
	s_waitcnt lgkmcnt(0)
	v_add_f32_e32 v81, v80, v81
	v_mbcnt_lo_u32_b32 v80, -1, 0
	v_mbcnt_hi_u32_b32 v80, -1, v80
	s_nop 0
	v_lshlrev_b32_e32 v80, 2, v80
	v_xor_b32_e32 v80, 32, v80
	ds_bpermute_b32 v82, v80, v81
	v_lshl_add_u32 v80, v70, 2, 16
	s_and_saveexec_b64 s[8:9], vcc
	s_cbranch_execz .LBB0_492
	s_waitcnt lgkmcnt(0)
	v_add_f32_e32 v81, v81, v82
	v_mul_f32_e32 v81, 0x3db504f3, v81
	ds_write_b32 v80, v81
.LBB0_492:
	s_or_b64 exec, exec, s[8:9]
	s_waitcnt lgkmcnt(0)
	v_add_u32_e32 v82, 4, v70
	v_ashrrev_i32_e32 v83, 31, v82
	v_lshlrev_b64 v[82:83], 11, v[82:83]
	v_lshl_add_u64 v[86:87], v[68:69], 0, v[82:83]
	s_nop 0
	v_mbcnt_lo_u32_b32 v81, -1, 0
	v_mbcnt_hi_u32_b32 v81, -1, v81
	s_waitcnt vmcnt(12)
	v_mul_f32_e32 v83, v165, v79
	v_fmac_f32_e32 v83, v164, v71
	v_fmac_f32_e32 v83, v166, v73
	v_fmac_f32_e32 v83, v167, v74
	v_fmac_f32_e32 v83, v168, v75
	v_fmac_f32_e32 v83, v169, v76
	v_lshlrev_b32_e32 v81, 2, v81
	v_fmac_f32_e32 v83, v170, v77
	v_xor_b32_e32 v81, 4, v81
	v_fmac_f32_e32 v83, v171, v78
	ds_bpermute_b32 v81, v81, v83
	v_mbcnt_lo_u32_b32 v82, -1, 0
	v_mbcnt_hi_u32_b32 v82, -1, v82
	s_waitcnt lgkmcnt(0)
	v_add_f32_e32 v81, v83, v81
	v_lshlrev_b32_e32 v82, 2, v82
	v_xor_b32_e32 v82, 8, v82
	ds_bpermute_b32 v82, v82, v81
	v_mbcnt_lo_u32_b32 v83, -1, 0
	v_mbcnt_hi_u32_b32 v83, -1, v83
	s_waitcnt lgkmcnt(0)
	v_add_f32_e32 v81, v81, v82
	v_lshlrev_b32_e32 v83, 2, v83
	v_xor_b32_e32 v83, 16, v83
	ds_bpermute_b32 v82, v83, v81
	v_mbcnt_lo_u32_b32 v83, -1, 0
	v_mbcnt_hi_u32_b32 v83, -1, v83
	s_waitcnt lgkmcnt(0)
	v_add_f32_e32 v81, v81, v82
	v_lshlrev_b32_e32 v83, 2, v83
	v_xor_b32_e32 v82, 32, v83
	ds_bpermute_b32 v82, v82, v81
	s_and_saveexec_b64 s[8:9], vcc
	s_cbranch_execz .LBB0_494
	s_waitcnt lgkmcnt(0)
	v_add_f32_e32 v81, v81, v82
	v_mul_f32_e32 v81, 0x3db504f3, v81
	ds_write_b32 v80, v81 offset:16
.LBB0_494:
	s_or_b64 exec, exec, s[8:9]
	s_waitcnt lgkmcnt(0)
	v_add_u32_e32 v82, 8, v70
	v_ashrrev_i32_e32 v83, 31, v82
	v_lshlrev_b64 v[82:83], 11, v[82:83]
	v_lshl_add_u64 v[86:87], v[68:69], 0, v[82:83]
	s_nop 0
	v_mbcnt_lo_u32_b32 v81, -1, 0
	v_mbcnt_hi_u32_b32 v81, -1, v81
	s_waitcnt vmcnt(10)
	v_mul_f32_e32 v83, v173, v79
	v_fmac_f32_e32 v83, v172, v71
	v_fmac_f32_e32 v83, v174, v73
	v_fmac_f32_e32 v83, v175, v74
	v_fmac_f32_e32 v83, v176, v75
	v_fmac_f32_e32 v83, v177, v76
	v_lshlrev_b32_e32 v81, 2, v81
	v_fmac_f32_e32 v83, v178, v77
	v_xor_b32_e32 v81, 4, v81
	v_fmac_f32_e32 v83, v179, v78
	ds_bpermute_b32 v81, v81, v83
	v_mbcnt_lo_u32_b32 v82, -1, 0
	v_mbcnt_hi_u32_b32 v82, -1, v82
	s_waitcnt lgkmcnt(0)
	v_add_f32_e32 v81, v83, v81
	v_lshlrev_b32_e32 v82, 2, v82
	v_xor_b32_e32 v82, 8, v82
	ds_bpermute_b32 v82, v82, v81
	v_mbcnt_lo_u32_b32 v83, -1, 0
	v_mbcnt_hi_u32_b32 v83, -1, v83
	s_waitcnt lgkmcnt(0)
	v_add_f32_e32 v81, v81, v82
	v_lshlrev_b32_e32 v83, 2, v83
	v_xor_b32_e32 v83, 16, v83
	ds_bpermute_b32 v82, v83, v81
	v_mbcnt_lo_u32_b32 v83, -1, 0
	v_mbcnt_hi_u32_b32 v83, -1, v83
	s_waitcnt lgkmcnt(0)
	v_add_f32_e32 v81, v81, v82
	v_lshlrev_b32_e32 v83, 2, v83
	v_xor_b32_e32 v82, 32, v83
	ds_bpermute_b32 v82, v82, v81
	s_and_saveexec_b64 s[8:9], vcc
	s_cbranch_execz .LBB0_496
	s_waitcnt lgkmcnt(0)
	v_add_f32_e32 v81, v81, v82
	v_mul_f32_e32 v81, 0x3db504f3, v81
	ds_write_b32 v80, v81 offset:32
.LBB0_496:
	s_or_b64 exec, exec, s[8:9]
	s_waitcnt lgkmcnt(0)
	v_add_u32_e32 v82, 12, v70
	v_ashrrev_i32_e32 v83, 31, v82
	v_lshlrev_b64 v[82:83], 11, v[82:83]
	v_lshl_add_u64 v[86:87], v[68:69], 0, v[82:83]
	s_nop 0
	v_mbcnt_lo_u32_b32 v81, -1, 0
	v_mbcnt_hi_u32_b32 v81, -1, v81
	s_waitcnt vmcnt(8)
	v_mul_f32_e32 v83, v181, v79
	v_fmac_f32_e32 v83, v180, v71
	v_fmac_f32_e32 v83, v182, v73
	v_fmac_f32_e32 v83, v183, v74
	v_fmac_f32_e32 v83, v184, v75
	v_fmac_f32_e32 v83, v185, v76
	v_lshlrev_b32_e32 v81, 2, v81
	v_fmac_f32_e32 v83, v186, v77
	v_xor_b32_e32 v81, 4, v81
	v_fmac_f32_e32 v83, v187, v78
	ds_bpermute_b32 v81, v81, v83
	v_mbcnt_lo_u32_b32 v82, -1, 0
	v_mbcnt_hi_u32_b32 v82, -1, v82
	s_waitcnt lgkmcnt(0)
	v_add_f32_e32 v81, v83, v81
	v_lshlrev_b32_e32 v82, 2, v82
	v_xor_b32_e32 v82, 8, v82
	ds_bpermute_b32 v82, v82, v81
	v_mbcnt_lo_u32_b32 v83, -1, 0
	v_mbcnt_hi_u32_b32 v83, -1, v83
	s_waitcnt lgkmcnt(0)
	v_add_f32_e32 v81, v81, v82
	v_lshlrev_b32_e32 v83, 2, v83
	v_xor_b32_e32 v83, 16, v83
	ds_bpermute_b32 v82, v83, v81
	v_mbcnt_lo_u32_b32 v83, -1, 0
	v_mbcnt_hi_u32_b32 v83, -1, v83
	s_waitcnt lgkmcnt(0)
	v_add_f32_e32 v81, v81, v82
	v_lshlrev_b32_e32 v83, 2, v83
	v_xor_b32_e32 v82, 32, v83
	ds_bpermute_b32 v82, v82, v81
	s_and_saveexec_b64 s[8:9], vcc
	s_cbranch_execz .LBB0_498
	s_waitcnt lgkmcnt(0)
	v_add_f32_e32 v81, v81, v82
	v_mul_f32_e32 v81, 0x3db504f3, v81
	ds_write_b32 v80, v81 offset:48
; __device__ __forceinline__ float shfl_xor_f(float v, int mask) { const int l = lane_fresh(); return __int_as_float(__builtin_amdgcn_ds_bpermute((l ^ mask) << 2, __float_as_int(v))); }
; __device__ __forceinline__ void attn_sample_item(const Params& p, int item, const int wv) {
;     ...
;     for (int it = 0; it < 8; ++it) {
;       const int mm = wid * 32 + it * 4 + ksub;
;       f32x4 k0 = *(const f32x4*)(Kc + (size_t)mm * 512 + dch * 8), k1 = *(const f32x4*)(Kc + (size_t)mm * 512 + dch * 8 + 4);
;       float d = q[0] * k0[0] + q[1] * k0[1] + q[2] * k0[2] + q[3] * k0[3] + q[4] * k1[0] + q[5] * k1[1] + q[6] * k1[2] + q[7] * k1[3];
;       d += shfl_xor_f(d, 1); d += shfl_xor_f(d, 2); d += shfl_xor_f(d, 4); d += shfl_xor_f(d, 8);
;       if (dch == 0) sc_l[mm] = d * 0.08838834764831845f;
;     }
.LBB0_498:
	s_or_b64 exec, exec, s[8:9]
	s_waitcnt lgkmcnt(0)
	v_add_u32_e32 v82, 16, v70
	v_ashrrev_i32_e32 v83, 31, v82
	v_lshlrev_b64 v[82:83], 11, v[82:83]
	v_lshl_add_u64 v[86:87], v[68:69], 0, v[82:83]
	s_nop 0
	v_mbcnt_lo_u32_b32 v81, -1, 0
	v_mbcnt_hi_u32_b32 v81, -1, v81
	s_waitcnt vmcnt(6)
	v_mul_f32_e32 v83, v189, v79
	v_fmac_f32_e32 v83, v188, v71
	v_fmac_f32_e32 v83, v190, v73
	v_fmac_f32_e32 v83, v191, v74
	v_fmac_f32_e32 v83, v192, v75
	v_fmac_f32_e32 v83, v193, v76
	v_lshlrev_b32_e32 v81, 2, v81
	v_fmac_f32_e32 v83, v194, v77
	v_xor_b32_e32 v81, 4, v81
	v_fmac_f32_e32 v83, v195, v78
	ds_bpermute_b32 v81, v81, v83
	v_mbcnt_lo_u32_b32 v82, -1, 0
	v_mbcnt_hi_u32_b32 v82, -1, v82
	s_waitcnt lgkmcnt(0)
	v_add_f32_e32 v81, v83, v81
	v_lshlrev_b32_e32 v82, 2, v82
	v_xor_b32_e32 v82, 8, v82
	ds_bpermute_b32 v82, v82, v81
	v_mbcnt_lo_u32_b32 v83, -1, 0
	v_mbcnt_hi_u32_b32 v83, -1, v83
	s_waitcnt lgkmcnt(0)
	v_add_f32_e32 v81, v81, v82
	v_lshlrev_b32_e32 v83, 2, v83
	v_xor_b32_e32 v83, 16, v83
	ds_bpermute_b32 v82, v83, v81
	v_mbcnt_lo_u32_b32 v83, -1, 0
	v_mbcnt_hi_u32_b32 v83, -1, v83
	s_waitcnt lgkmcnt(0)
	v_add_f32_e32 v81, v81, v82
	v_lshlrev_b32_e32 v83, 2, v83
	v_xor_b32_e32 v82, 32, v83
	ds_bpermute_b32 v82, v82, v81
	s_and_saveexec_b64 s[8:9], vcc
	s_cbranch_execz .LBB0_500
	s_waitcnt lgkmcnt(0)
	v_add_f32_e32 v81, v81, v82
	v_mul_f32_e32 v81, 0x3db504f3, v81
	ds_write_b32 v80, v81 offset:64
.LBB0_500:
	s_or_b64 exec, exec, s[8:9]
	s_waitcnt lgkmcnt(0)
	v_add_u32_e32 v82, 20, v70
	v_ashrrev_i32_e32 v83, 31, v82
	v_lshlrev_b64 v[82:83], 11, v[82:83]
	v_lshl_add_u64 v[86:87], v[68:69], 0, v[82:83]
	s_nop 0
	v_mbcnt_lo_u32_b32 v81, -1, 0
	v_mbcnt_hi_u32_b32 v81, -1, v81
	s_waitcnt vmcnt(4)
	v_mul_f32_e32 v83, v197, v79
	v_fmac_f32_e32 v83, v196, v71
	v_fmac_f32_e32 v83, v198, v73
	v_fmac_f32_e32 v83, v199, v74
	v_fmac_f32_e32 v83, v200, v75
	v_fmac_f32_e32 v83, v201, v76
	v_lshlrev_b32_e32 v81, 2, v81
	v_fmac_f32_e32 v83, v202, v77
	v_xor_b32_e32 v81, 4, v81
	v_fmac_f32_e32 v83, v203, v78
	ds_bpermute_b32 v81, v81, v83
	v_mbcnt_lo_u32_b32 v82, -1, 0
	v_mbcnt_hi_u32_b32 v82, -1, v82
	s_waitcnt lgkmcnt(0)
	v_add_f32_e32 v81, v83, v81
	v_lshlrev_b32_e32 v82, 2, v82
	v_xor_b32_e32 v82, 8, v82
	ds_bpermute_b32 v82, v82, v81
	v_mbcnt_lo_u32_b32 v83, -1, 0
	v_mbcnt_hi_u32_b32 v83, -1, v83
	s_waitcnt lgkmcnt(0)
	v_add_f32_e32 v81, v81, v82
	v_lshlrev_b32_e32 v83, 2, v83
	v_xor_b32_e32 v83, 16, v83
	ds_bpermute_b32 v82, v83, v81
	v_mbcnt_lo_u32_b32 v83, -1, 0
	v_mbcnt_hi_u32_b32 v83, -1, v83
	s_waitcnt lgkmcnt(0)
	v_add_f32_e32 v81, v81, v82
	v_lshlrev_b32_e32 v83, 2, v83
	v_xor_b32_e32 v82, 32, v83
	ds_bpermute_b32 v82, v82, v81
	s_and_saveexec_b64 s[8:9], vcc
	s_cbranch_execz .LBB0_502
	s_waitcnt lgkmcnt(0)
	v_add_f32_e32 v81, v81, v82
	v_mul_f32_e32 v81, 0x3db504f3, v81
	ds_write_b32 v80, v81 offset:80
.LBB0_502:
	s_or_b64 exec, exec, s[8:9]
	s_waitcnt lgkmcnt(0)
	v_add_u32_e32 v82, 24, v70
	v_ashrrev_i32_e32 v83, 31, v82
	v_lshlrev_b64 v[82:83], 11, v[82:83]
	v_lshl_add_u64 v[86:87], v[68:69], 0, v[82:83]
	s_nop 0
	v_mbcnt_lo_u32_b32 v81, -1, 0
	v_mbcnt_hi_u32_b32 v81, -1, v81
	s_waitcnt vmcnt(2)
	v_mul_f32_e32 v83, v205, v79
	v_fmac_f32_e32 v83, v204, v71
	v_fmac_f32_e32 v83, v206, v73
	v_fmac_f32_e32 v83, v207, v74
	v_fmac_f32_e32 v83, v208, v75
	v_fmac_f32_e32 v83, v209, v76
	v_lshlrev_b32_e32 v81, 2, v81
	v_fmac_f32_e32 v83, v210, v77
	v_xor_b32_e32 v81, 4, v81
	v_fmac_f32_e32 v83, v211, v78
	ds_bpermute_b32 v81, v81, v83
	v_mbcnt_lo_u32_b32 v82, -1, 0
	v_mbcnt_hi_u32_b32 v82, -1, v82
	s_waitcnt lgkmcnt(0)
	v_add_f32_e32 v81, v83, v81
	v_lshlrev_b32_e32 v82, 2, v82
	v_xor_b32_e32 v82, 8, v82
	ds_bpermute_b32 v82, v82, v81
	v_mbcnt_lo_u32_b32 v83, -1, 0
	v_mbcnt_hi_u32_b32 v83, -1, v83
	s_waitcnt lgkmcnt(0)
	v_add_f32_e32 v81, v81, v82
	v_lshlrev_b32_e32 v83, 2, v83
	v_xor_b32_e32 v83, 16, v83
	ds_bpermute_b32 v82, v83, v81
	v_mbcnt_lo_u32_b32 v83, -1, 0
	v_mbcnt_hi_u32_b32 v83, -1, v83
	s_waitcnt lgkmcnt(0)
	v_add_f32_e32 v81, v81, v82
	v_lshlrev_b32_e32 v83, 2, v83
	v_xor_b32_e32 v82, 32, v83
	ds_bpermute_b32 v82, v82, v81
	s_and_saveexec_b64 s[8:9], vcc
	s_cbranch_execz .LBB0_504
	s_waitcnt lgkmcnt(0)
	v_add_f32_e32 v81, v81, v82
	v_mul_f32_e32 v81, 0x3db504f3, v81
	ds_write_b32 v80, v81 offset:96
.LBB0_504:
	s_or_b64 exec, exec, s[8:9]
	s_waitcnt lgkmcnt(0)
	v_add_u32_e32 v82, 28, v70
	v_ashrrev_i32_e32 v83, 31, v82
	v_lshlrev_b64 v[82:83], 11, v[82:83]
	v_lshl_add_u64 v[68:69], v[68:69], 0, v[82:83]
	v_mbcnt_lo_u32_b32 v68, -1, 0
	v_mbcnt_hi_u32_b32 v68, -1, v68
	v_mbcnt_lo_u32_b32 v70, -1, 0
	v_mbcnt_hi_u32_b32 v70, -1, v70
	s_waitcnt vmcnt(0)
	v_mul_f32_e32 v69, v213, v79
	v_fmac_f32_e32 v69, v212, v71
	v_fmac_f32_e32 v69, v214, v73
	v_fmac_f32_e32 v69, v215, v74
	v_fmac_f32_e32 v69, v216, v75
	v_fmac_f32_e32 v69, v217, v76
	v_lshlrev_b32_e32 v68, 2, v68
	v_fmac_f32_e32 v69, v218, v77
	v_xor_b32_e32 v68, 4, v68
	v_fmac_f32_e32 v69, v219, v78
	ds_bpermute_b32 v68, v68, v69
	v_lshlrev_b32_e32 v70, 2, v70
	v_xor_b32_e32 v70, 8, v70
	s_waitcnt lgkmcnt(0)
	v_add_f32_e32 v68, v69, v68
	ds_bpermute_b32 v69, v70, v68
	v_mbcnt_lo_u32_b32 v70, -1, 0
	v_mbcnt_hi_u32_b32 v70, -1, v70
	s_waitcnt lgkmcnt(0)
	v_add_f32_e32 v68, v68, v69
	v_lshlrev_b32_e32 v70, 2, v70
	v_xor_b32_e32 v70, 16, v70
	ds_bpermute_b32 v69, v70, v68
	v_mbcnt_lo_u32_b32 v70, -1, 0
	v_mbcnt_hi_u32_b32 v70, -1, v70
	s_waitcnt lgkmcnt(0)
	v_add_f32_e32 v68, v68, v69
	v_lshlrev_b32_e32 v70, 2, v70
	v_xor_b32_e32 v69, 32, v70
	ds_bpermute_b32 v69, v69, v68
	s_and_saveexec_b64 s[8:9], vcc
	s_cbranch_execz .LBB0_506
	s_waitcnt lgkmcnt(0)
	v_add_f32_e32 v68, v68, v69
	v_mul_f32_e32 v68, 0x3db504f3, v68
	ds_write_b32 v80, v68 offset:112

; __device__ __forceinline__ void attn_sample_item(const Params& p, int item, const int wv) {
;     ...
;   const float* Kc = p.in[3] + ((size_t)b * 256 * 4 + h) * 128;
;   const float* Vc = p.in[4] + ((size_t)b * 256 * 4 + h) * 128;
;   const int vdch = tid & 31, vmg = tid >> 5;
;   f32x4 vreg[16];
; #pragma unroll
;   for (int i = 0; i < 16; ++i) vreg[i] = *(const f32x4*)(Vc + (size_t)(vmg * 16 + i) * 512 + vdch * 4);
;   __syncthreads();
.LBB0_511:
	s_andn2_b64 vcc, exec, s[0:1]
	s_cbranch_vccnz .LBB0_533
	s_ashr_i32 s0, s57, 2
	s_lshl_b32 s5, s57, 7
	s_ashr_i32 s1, s0, 31
	s_and_b32 s5, s5, 0x180
	s_lshl_b64 s[8:9], s[0:1], 19
	s_lshl_b32 s1, s5, 2
	v_readlane_b32 s12, v251, 6
	s_or_b32 s1, s8, s1
	v_readlane_b32 s20, v251, 14
	v_readlane_b32 s21, v251, 15
	s_add_u32 s10, s20, s1
	v_readlane_b32 s18, v251, 12
	s_addc_u32 s11, s21, s9
	s_addk_i32 s0, 0x4000
	v_mbcnt_lo_u32_b32 v72, -1, 0
	v_mbcnt_hi_u32_b32 v72, -1, v72
	v_readlane_b32 s19, v251, 13
	v_and_b32_e32 v0, 31, v72
	s_add_u32 s8, s18, s1
	v_lshlrev_b32_e32 v66, 4, v0
	v_mov_b32_e32 v67, 0
	s_addc_u32 s9, s19, s9
	s_ashr_i32 s1, s0, 31
	v_add_u32_e32 v64, s82, v72
	v_lshl_add_u64 v[58:59], s[10:11], 0, v[66:67]
	s_lshl_b64 s[10:11], s[0:1], 10
	v_ashrrev_i32_e32 v65, 5, v64
	s_add_u32 s7, s48, s10
	v_lshlrev_b32_e32 v56, 4, v65
	s_addc_u32 s11, s49, s11
	s_lshl_b32 s5, s5, 1
	v_ashrrev_i32_e32 v57, 31, v56
	v_and_b32_e32 v88, 15, v72
	s_add_u32 s10, s7, s5
	s_waitcnt lgkmcnt(0)
	v_lshlrev_b64 v[0:1], 11, v[56:57]
	v_or_b32_e32 v2, 1, v56
	v_or_b32_e32 v8, 2, v56
	v_or_b32_e32 v10, 3, v56
	v_or_b32_e32 v16, 4, v56
	v_or_b32_e32 v18, 5, v56
	v_or_b32_e32 v24, 6, v56
	v_or_b32_e32 v26, 7, v56
	v_or_b32_e32 v32, 8, v56
	v_or_b32_e32 v34, 9, v56
	v_or_b32_e32 v40, 10, v56
	v_or_b32_e32 v42, 11, v56
	v_or_b32_e32 v48, 12, v56
	v_or_b32_e32 v50, 13, v56
	v_or_b32_e32 v60, 14, v56
	v_or_b32_e32 v56, 15, v56
	s_addc_u32 s11, s11, 0
	v_lshlrev_b32_e32 v68, 4, v88
	v_mov_b32_e32 v69, v67
	v_ashrrev_i32_e32 v3, 31, v2
	v_ashrrev_i32_e32 v9, 31, v8
	v_ashrrev_i32_e32 v11, 31, v10
	v_ashrrev_i32_e32 v17, 31, v16
	v_ashrrev_i32_e32 v19, 31, v18
	v_ashrrev_i32_e32 v25, 31, v24
	v_ashrrev_i32_e32 v27, 31, v26
	v_ashrrev_i32_e32 v33, 31, v32
	v_ashrrev_i32_e32 v35, 31, v34
	v_ashrrev_i32_e32 v41, 31, v40
	v_ashrrev_i32_e32 v43, 31, v42
	v_ashrrev_i32_e32 v49, 31, v48
	v_ashrrev_i32_e32 v51, 31, v50
	v_ashrrev_i32_e32 v61, 31, v60
	v_ashrrev_i32_e32 v57, 31, v56
	v_lshl_add_u64 v[68:69], s[10:11], 0, v[68:69]
	s_mov_b32 s7, 0x2040000
	v_lshlrev_b64 v[2:3], 11, v[2:3]
	v_lshlrev_b64 v[8:9], 11, v[8:9]
	v_lshlrev_b64 v[10:11], 11, v[10:11]
	v_lshlrev_b64 v[16:17], 11, v[16:17]
	v_lshlrev_b64 v[18:19], 11, v[18:19]
	v_lshlrev_b64 v[24:25], 11, v[24:25]
	v_lshlrev_b64 v[26:27], 11, v[26:27]
	v_lshlrev_b64 v[32:33], 11, v[32:33]
	v_lshlrev_b64 v[34:35], 11, v[34:35]
	v_lshlrev_b64 v[40:41], 11, v[40:41]
	v_lshlrev_b64 v[42:43], 11, v[42:43]
	v_lshlrev_b64 v[48:49], 11, v[48:49]
	v_lshlrev_b64 v[50:51], 11, v[50:51]
	v_lshlrev_b64 v[60:61], 11, v[60:61]
	v_lshlrev_b64 v[56:57], 11, v[56:57]
	v_ashrrev_i32_e32 v70, 4, v72
	v_add_co_u32_e32 v68, vcc, s7, v68
	v_lshl_add_u64 v[0:1], v[58:59], 0, v[0:1]
	v_lshl_add_u64 v[2:3], v[58:59], 0, v[2:3]
	v_lshl_add_u64 v[8:9], v[58:59], 0, v[8:9]
	v_lshl_add_u64 v[10:11], v[58:59], 0, v[10:11]
	v_lshl_add_u64 v[16:17], v[58:59], 0, v[16:17]
	v_lshl_add_u64 v[18:19], v[58:59], 0, v[18:19]
	v_lshl_add_u64 v[24:25], v[58:59], 0, v[24:25]
	v_lshl_add_u64 v[26:27], v[58:59], 0, v[26:27]
	v_lshl_add_u64 v[32:33], v[58:59], 0, v[32:33]
	v_lshl_add_u64 v[34:35], v[58:59], 0, v[34:35]
	v_lshl_add_u64 v[40:41], v[58:59], 0, v[40:41]
	v_lshl_add_u64 v[42:43], v[58:59], 0, v[42:43]
	v_lshl_add_u64 v[48:49], v[58:59], 0, v[48:49]
	v_lshl_add_u64 v[50:51], v[58:59], 0, v[50:51]
	v_lshl_add_u64 v[60:61], v[58:59], 0, v[60:61]
	v_lshl_add_u64 v[56:57], v[58:59], 0, v[56:57]
	v_addc_co_u32_e32 v69, vcc, 0, v69, vcc
	v_lshl_add_u32 v70, s83, 5, v70
	global_load_dwordx4 v[4:7], v[0:1], off
	s_nop 0
	global_load_dwordx4 v[0:3], v[2:3], off
	s_nop 0
	global_load_dwordx4 v[12:15], v[8:9], off
	s_nop 0
	global_load_dwordx4 v[8:11], v[10:11], off
	s_nop 0
	global_load_dwordx4 v[20:23], v[16:17], off
	s_nop 0
	global_load_dwordx4 v[16:19], v[18:19], off
	s_nop 0
	global_load_dwordx4 v[28:31], v[24:25], off
	s_nop 0
	global_load_dwordx4 v[24:27], v[26:27], off
	s_nop 0
	global_load_dwordx4 v[36:39], v[32:33], off
	s_nop 0
	global_load_dwordx4 v[32:35], v[34:35], off
	s_nop 0
	global_load_dwordx4 v[44:47], v[40:41], off
	s_nop 0
	global_load_dwordx4 v[40:43], v[42:43], off
	s_nop 0
	global_load_dwordx4 v[52:55], v[48:49], off
	s_nop 0
	global_load_dwordx4 v[48:51], v[50:51], off
	s_nop 0
	global_load_dwordx4 v[60:63], v[60:61], off
	s_nop 0
	global_load_dwordx4 v[56:59], v[56:57], off
	s_barrier
; __device__ __forceinline__ float bflo(unsigned w) { return __uint_as_float(w << 16); }
; __device__ __forceinline__ float bfhi(unsigned w) { return __uint_as_float(w & 0xffff0000u); }
; __device__ __forceinline__ float shfl_xor_f(float v, int mask) { const int l = lane_fresh(); return __int_as_float(__builtin_amdgcn_ds_bpermute((l ^ mask) << 2, __float_as_int(v))); }
; __device__ __forceinline__ void attn_sample_item(const Params& p, int item, const int wv) {
;     ...
;     const int dch = lane & 15, ksub = lane >> 4;
;     u32x4 qw = *(const u32x4*)(Q + (size_t)tok * 512 + h * 128 + dch * 8);
;     float q[8] = {bflo(qw.x), bfhi(qw.x), bflo(qw.y), bfhi(qw.y), bflo(qw.z), bfhi(qw.z), bflo(qw.w), bfhi(qw.w)};
; #pragma unroll
;     for (int it = 0; it < 8; ++it) {
;       const int mm = wid * 32 + it * 4 + ksub;
;       f32x4 k0 = *(const f32x4*)(Kc + (size_t)mm * 512 + dch * 8), k1 = *(const f32x4*)(Kc + (size_t)mm * 512 + dch * 8 + 4);
;       float d = q[0] * k0[0] + q[1] * k0[1] + q[2] * k0[2] + q[3] * k0[3] + q[4] * k1[0] + q[5] * k1[1] + q[6] * k1[2] + q[7] * k1[3];
;       d += shfl_xor_f(d, 1); d += shfl_xor_f(d, 2); d += shfl_xor_f(d, 4); d += shfl_xor_f(d, 8);
;       if (dch == 0) sc_l[mm] = d * 0.08838834764831845f;
;     }
	global_load_dwordx4 v[74:77], v[68:69], off
	v_lshlrev_b32_e32 v68, 5, v88
	v_mov_b32_e32 v69, v67
	v_ashrrev_i32_e32 v71, 31, v70
	v_lshl_add_u64 v[68:69], s[8:9], 0, v[68:69]
	v_lshlrev_b64 v[78:79], 11, v[70:71]
	v_lshl_add_u64 v[78:79], v[68:69], 0, v[78:79]
	global_load_dwordx4 v[80:83], v[78:79], off
	global_load_dwordx4 v[84:87], v[78:79], off offset:16
	v_mov_b32_e32 v221, 0
	v_mov_b32_e32 v220, 0x2000
	v_lshl_add_u64 v[222:223], v[220:221], 0, v[78:79]
	global_load_dwordx4 v[164:167], v[222:223], off
	global_load_dwordx4 v[168:171], v[222:223], off offset:16
	v_mov_b32_e32 v220, 0x4000
	v_lshl_add_u64 v[222:223], v[220:221], 0, v[78:79]
	global_load_dwordx4 v[172:175], v[222:223], off
	global_load_dwordx4 v[176:179], v[222:223], off offset:16
	v_mov_b32_e32 v220, 0x6000
	v_lshl_add_u64 v[222:223], v[220:221], 0, v[78:79]
	global_load_dwordx4 v[180:183], v[222:223], off
	global_load_dwordx4 v[184:187], v[222:223], off offset:16
	v_mov_b32_e32 v220, 0x8000
	v_lshl_add_u64 v[222:223], v[220:221], 0, v[78:79]
	global_load_dwordx4 v[188:191], v[222:223], off
	global_load_dwordx4 v[192:195], v[222:223], off offset:16
	v_mov_b32_e32 v220, 0xa000
	v_lshl_add_u64 v[222:223], v[220:221], 0, v[78:79]
	global_load_dwordx4 v[196:199], v[222:223], off
	global_load_dwordx4 v[200:203], v[222:223], off offset:16
	v_mov_b32_e32 v220, 0xc000
	v_lshl_add_u64 v[222:223], v[220:221], 0, v[78:79]
	global_load_dwordx4 v[204:207], v[222:223], off
	global_load_dwordx4 v[208:211], v[222:223], off offset:16
	v_mov_b32_e32 v220, 0xe000
	v_lshl_add_u64 v[222:223], v[220:221], 0, v[78:79]
	global_load_dwordx4 v[212:215], v[222:223], off
	global_load_dwordx4 v[216:219], v[222:223], off offset:16
	v_cmp_eq_u32_e32 vcc, 0, v88
	v_readlane_b32 s13, v251, 7
	v_readlane_b32 s14, v251, 8
	v_readlane_b32 s15, v251, 9
	v_readlane_b32 s16, v251, 10
	v_readlane_b32 s17, v251, 11
	v_readlane_b32 s22, v251, 16
	v_readlane_b32 s23, v251, 17
	v_readlane_b32 s24, v251, 18
	v_readlane_b32 s25, v251, 19
	v_readlane_b32 s26, v251, 20
	v_readlane_b32 s27, v251, 21
	s_waitcnt vmcnt(16)
	v_and_b32_e32 v78, 0xffff0000, v74
	v_lshlrev_b32_e32 v67, 16, v74
	v_lshlrev_b32_e32 v71, 16, v75
	v_and_b32_e32 v73, 0xffff0000, v75
	v_lshlrev_b32_e32 v74, 16, v76
	v_and_b32_e32 v75, 0xffff0000, v76
	s_waitcnt vmcnt(15)
	v_mul_f32_e32 v79, v81, v78
	v_fmac_f32_e32 v79, v80, v67
	v_fmac_f32_e32 v79, v82, v71
	v_fmac_f32_e32 v79, v83, v73
	s_waitcnt vmcnt(14)
	v_fmac_f32_e32 v79, v84, v74
	v_lshlrev_b32_e32 v76, 16, v77
	v_fmac_f32_e32 v79, v85, v75
	v_mbcnt_lo_u32_b32 v80, -1, 0
	v_mbcnt_hi_u32_b32 v80, -1, v80
	v_and_b32_e32 v77, 0xffff0000, v77
	v_fmac_f32_e32 v79, v86, v76
	v_lshlrev_b32_e32 v80, 2, v80
	v_fmac_f32_e32 v79, v87, v77
	v_xor_b32_e32 v80, 4, v80
	ds_bpermute_b32 v80, v80, v79
	s_waitcnt lgkmcnt(0)
	v_add_f32_e32 v79, v79, v80
	v_mbcnt_lo_u32_b32 v80, -1, 0
	v_mbcnt_hi_u32_b32 v80, -1, v80
	s_nop 0
	v_lshlrev_b32_e32 v80, 2, v80
	v_xor_b32_e32 v80, 8, v80
	ds_bpermute_b32 v80, v80, v79
	s_waitcnt lgkmcnt(0)
	v_add_f32_e32 v79, v79, v80
	v_mbcnt_lo_u32_b32 v80, -1, 0
	v_mbcnt_hi_u32_b32 v80, -1, v80
	s_nop 0
	v_lshlrev_b32_e32 v80, 2, v80
	v_xor_b32_e32 v80, 16, v80
	ds_bpermute_b32 v80, v80, v79
	s_waitcnt lgkmcnt(0)
	v_add_f32_e32 v80, v79, v80
	v_mbcnt_lo_u32_b32 v79, -1, 0
	v_mbcnt_hi_u32_b32 v79, -1, v79
	s_nop 0
	v_lshlrev_b32_e32 v79, 2, v79
	v_xor_b32_e32 v79, 32, v79
	ds_bpermute_b32 v81, v79, v80
	v_lshl_add_u32 v79, v70, 2, 16
	s_and_saveexec_b64 s[8:9], vcc
	s_cbranch_execz .LBB0_514
	s_waitcnt lgkmcnt(0)
	v_add_f32_e32 v80, v80, v81
	v_mul_f32_e32 v80, 0x3db504f3, v80
	ds_write_b32 v79, v80
.LBB0_514:
	s_or_b64 exec, exec, s[8:9]
	v_add_u32_e32 v80, 4, v70
	s_waitcnt lgkmcnt(0)
	v_ashrrev_i32_e32 v81, 31, v80
	v_lshlrev_b64 v[80:81], 11, v[80:81]
	v_lshl_add_u64 v[84:85], v[68:69], 0, v[80:81]
	s_nop 0
	v_mbcnt_lo_u32_b32 v88, -1, 0
	v_mbcnt_hi_u32_b32 v88, -1, v88
	s_waitcnt vmcnt(12)
	v_mul_f32_e32 v81, v165, v78
	v_fmac_f32_e32 v81, v164, v67
	v_fmac_f32_e32 v81, v166, v71
	v_fmac_f32_e32 v81, v167, v73
	v_fmac_f32_e32 v81, v168, v74
	v_fmac_f32_e32 v81, v169, v75
	v_lshlrev_b32_e32 v88, 2, v88
	v_fmac_f32_e32 v81, v170, v76
	v_xor_b32_e32 v88, 4, v88
	v_fmac_f32_e32 v81, v171, v77
	ds_bpermute_b32 v80, v88, v81
	v_mbcnt_lo_u32_b32 v82, -1, 0
	v_mbcnt_hi_u32_b32 v82, -1, v82
	s_waitcnt lgkmcnt(0)
	v_add_f32_e32 v80, v81, v80
	v_lshlrev_b32_e32 v82, 2, v82
	v_xor_b32_e32 v82, 8, v82
	ds_bpermute_b32 v81, v82, v80
	v_mbcnt_lo_u32_b32 v82, -1, 0
	v_mbcnt_hi_u32_b32 v82, -1, v82
	s_waitcnt lgkmcnt(0)
	v_add_f32_e32 v80, v80, v81
	v_lshlrev_b32_e32 v82, 2, v82
	v_xor_b32_e32 v82, 16, v82
	ds_bpermute_b32 v81, v82, v80
	v_mbcnt_lo_u32_b32 v82, -1, 0
	v_mbcnt_hi_u32_b32 v82, -1, v82
	s_waitcnt lgkmcnt(0)
	v_add_f32_e32 v80, v80, v81
	v_lshlrev_b32_e32 v82, 2, v82
	v_xor_b32_e32 v81, 32, v82
	ds_bpermute_b32 v81, v81, v80
	s_and_saveexec_b64 s[8:9], vcc
	s_cbranch_execz .LBB0_516
	s_waitcnt lgkmcnt(0)
	v_add_f32_e32 v80, v80, v81
	v_mul_f32_e32 v80, 0x3db504f3, v80
	ds_write_b32 v79, v80 offset:16
; __device__ __forceinline__ float shfl_xor_f(float v, int mask) { const int l = lane_fresh(); return __int_as_float(__builtin_amdgcn_ds_bpermute((l ^ mask) << 2, __float_as_int(v))); }
; __device__ __forceinline__ void attn_sample_item(const Params& p, int item, const int wv) {
;     ...
;     for (int it = 0; it < 8; ++it) {
;       const int mm = wid * 32 + it * 4 + ksub;
;       f32x4 k0 = *(const f32x4*)(Kc + (size_t)mm * 512 + dch * 8), k1 = *(const f32x4*)(Kc + (size_t)mm * 512 + dch * 8 + 4);
;       float d = q[0] * k0[0] + q[1] * k0[1] + q[2] * k0[2] + q[3] * k0[3] + q[4] * k1[0] + q[5] * k1[1] + q[6] * k1[2] + q[7] * k1[3];
;       d += shfl_xor_f(d, 1); d += shfl_xor_f(d, 2); d += shfl_xor_f(d, 4); d += shfl_xor_f(d, 8);
;       if (dch == 0) sc_l[mm] = d * 0.08838834764831845f;
;     }
.LBB0_516:
	s_or_b64 exec, exec, s[8:9]
	v_add_u32_e32 v80, 8, v70
	s_waitcnt lgkmcnt(0)
	v_ashrrev_i32_e32 v81, 31, v80
	v_lshlrev_b64 v[80:81], 11, v[80:81]
	v_lshl_add_u64 v[84:85], v[68:69], 0, v[80:81]
	s_nop 0
	v_mbcnt_lo_u32_b32 v88, -1, 0
	v_mbcnt_hi_u32_b32 v88, -1, v88
	s_waitcnt vmcnt(10)
	v_mul_f32_e32 v81, v173, v78
	v_fmac_f32_e32 v81, v172, v67
	v_fmac_f32_e32 v81, v174, v71
	v_fmac_f32_e32 v81, v175, v73
	v_fmac_f32_e32 v81, v176, v74
	v_fmac_f32_e32 v81, v177, v75
	v_lshlrev_b32_e32 v88, 2, v88
	v_fmac_f32_e32 v81, v178, v76
	v_xor_b32_e32 v88, 4, v88
	v_fmac_f32_e32 v81, v179, v77
	ds_bpermute_b32 v80, v88, v81
	v_mbcnt_lo_u32_b32 v82, -1, 0
	v_mbcnt_hi_u32_b32 v82, -1, v82
	s_waitcnt lgkmcnt(0)
	v_add_f32_e32 v80, v81, v80
	v_lshlrev_b32_e32 v82, 2, v82
	v_xor_b32_e32 v82, 8, v82
	ds_bpermute_b32 v81, v82, v80
	v_mbcnt_lo_u32_b32 v82, -1, 0
	v_mbcnt_hi_u32_b32 v82, -1, v82
	s_waitcnt lgkmcnt(0)
	v_add_f32_e32 v80, v80, v81
	v_lshlrev_b32_e32 v82, 2, v82
	v_xor_b32_e32 v82, 16, v82
	ds_bpermute_b32 v81, v82, v80
	v_mbcnt_lo_u32_b32 v82, -1, 0
	v_mbcnt_hi_u32_b32 v82, -1, v82
	s_waitcnt lgkmcnt(0)
	v_add_f32_e32 v80, v80, v81
	v_lshlrev_b32_e32 v82, 2, v82
	v_xor_b32_e32 v81, 32, v82
	ds_bpermute_b32 v81, v81, v80
	s_and_saveexec_b64 s[8:9], vcc
	s_cbranch_execz .LBB0_518
	s_waitcnt lgkmcnt(0)
	v_add_f32_e32 v80, v80, v81
	v_mul_f32_e32 v80, 0x3db504f3, v80
	ds_write_b32 v79, v80 offset:32
.LBB0_518:
	s_or_b64 exec, exec, s[8:9]
	v_add_u32_e32 v80, 12, v70
	s_waitcnt lgkmcnt(0)
	v_ashrrev_i32_e32 v81, 31, v80
	v_lshlrev_b64 v[80:81], 11, v[80:81]
	v_lshl_add_u64 v[84:85], v[68:69], 0, v[80:81]
	s_nop 0
	v_mbcnt_lo_u32_b32 v88, -1, 0
	v_mbcnt_hi_u32_b32 v88, -1, v88
	s_waitcnt vmcnt(8)
	v_mul_f32_e32 v81, v181, v78
	v_fmac_f32_e32 v81, v180, v67
	v_fmac_f32_e32 v81, v182, v71
	v_fmac_f32_e32 v81, v183, v73
	v_fmac_f32_e32 v81, v184, v74
	v_fmac_f32_e32 v81, v185, v75
	v_lshlrev_b32_e32 v88, 2, v88
	v_fmac_f32_e32 v81, v186, v76
	v_xor_b32_e32 v88, 4, v88
	v_fmac_f32_e32 v81, v187, v77
	ds_bpermute_b32 v80, v88, v81
	v_mbcnt_lo_u32_b32 v82, -1, 0
	v_mbcnt_hi_u32_b32 v82, -1, v82
	s_waitcnt lgkmcnt(0)
	v_add_f32_e32 v80, v81, v80
	v_lshlrev_b32_e32 v82, 2, v82
	v_xor_b32_e32 v82, 8, v82
	ds_bpermute_b32 v81, v82, v80
	v_mbcnt_lo_u32_b32 v82, -1, 0
	v_mbcnt_hi_u32_b32 v82, -1, v82
	s_waitcnt lgkmcnt(0)
	v_add_f32_e32 v80, v80, v81
	v_lshlrev_b32_e32 v82, 2, v82
	v_xor_b32_e32 v82, 16, v82
	ds_bpermute_b32 v81, v82, v80
	v_mbcnt_lo_u32_b32 v82, -1, 0
	v_mbcnt_hi_u32_b32 v82, -1, v82
	s_waitcnt lgkmcnt(0)
	v_add_f32_e32 v80, v80, v81
	v_lshlrev_b32_e32 v82, 2, v82
	v_xor_b32_e32 v81, 32, v82
	ds_bpermute_b32 v81, v81, v80
	s_and_saveexec_b64 s[8:9], vcc
	s_cbranch_execz .LBB0_520
	s_waitcnt lgkmcnt(0)
	v_add_f32_e32 v80, v80, v81
	v_mul_f32_e32 v80, 0x3db504f3, v80
	ds_write_b32 v79, v80 offset:48
.LBB0_520:
	s_or_b64 exec, exec, s[8:9]
	v_add_u32_e32 v80, 16, v70
	s_waitcnt lgkmcnt(0)
	v_ashrrev_i32_e32 v81, 31, v80
	v_lshlrev_b64 v[80:81], 11, v[80:81]
	v_lshl_add_u64 v[84:85], v[68:69], 0, v[80:81]
	s_nop 0
	v_mbcnt_lo_u32_b32 v88, -1, 0
	v_mbcnt_hi_u32_b32 v88, -1, v88
	s_waitcnt vmcnt(6)
	v_mul_f32_e32 v81, v189, v78
	v_fmac_f32_e32 v81, v188, v67
	v_fmac_f32_e32 v81, v190, v71
	v_fmac_f32_e32 v81, v191, v73
	v_fmac_f32_e32 v81, v192, v74
	v_fmac_f32_e32 v81, v193, v75
	v_lshlrev_b32_e32 v88, 2, v88
	v_fmac_f32_e32 v81, v194, v76
	v_xor_b32_e32 v88, 4, v88
	v_fmac_f32_e32 v81, v195, v77
	ds_bpermute_b32 v80, v88, v81
	v_mbcnt_lo_u32_b32 v82, -1, 0
	v_mbcnt_hi_u32_b32 v82, -1, v82
	s_waitcnt lgkmcnt(0)
	v_add_f32_e32 v80, v81, v80
	v_lshlrev_b32_e32 v82, 2, v82
	v_xor_b32_e32 v82, 8, v82
	ds_bpermute_b32 v81, v82, v80
	v_mbcnt_lo_u32_b32 v82, -1, 0
	v_mbcnt_hi_u32_b32 v82, -1, v82
	s_waitcnt lgkmcnt(0)
	v_add_f32_e32 v80, v80, v81
	v_lshlrev_b32_e32 v82, 2, v82
	v_xor_b32_e32 v82, 16, v82
	ds_bpermute_b32 v81, v82, v80
	v_mbcnt_lo_u32_b32 v82, -1, 0
	v_mbcnt_hi_u32_b32 v82, -1, v82
	s_waitcnt lgkmcnt(0)
	v_add_f32_e32 v80, v80, v81
	v_lshlrev_b32_e32 v82, 2, v82
	v_xor_b32_e32 v81, 32, v82
	ds_bpermute_b32 v81, v81, v80
	s_and_saveexec_b64 s[8:9], vcc
	s_cbranch_execz .LBB0_522
	s_waitcnt lgkmcnt(0)
	v_add_f32_e32 v80, v80, v81
	v_mul_f32_e32 v80, 0x3db504f3, v80
	ds_write_b32 v79, v80 offset:64
; __device__ __forceinline__ float shfl_xor_f(float v, int mask) { const int l = lane_fresh(); return __int_as_float(__builtin_amdgcn_ds_bpermute((l ^ mask) << 2, __float_as_int(v))); }
; __device__ __forceinline__ void attn_sample_item(const Params& p, int item, const int wv) {
;     ...
;     for (int it = 0; it < 8; ++it) {
;       const int mm = wid * 32 + it * 4 + ksub;
;       f32x4 k0 = *(const f32x4*)(Kc + (size_t)mm * 512 + dch * 8), k1 = *(const f32x4*)(Kc + (size_t)mm * 512 + dch * 8 + 4);
;       float d = q[0] * k0[0] + q[1] * k0[1] + q[2] * k0[2] + q[3] * k0[3] + q[4] * k1[0] + q[5] * k1[1] + q[6] * k1[2] + q[7] * k1[3];
;       d += shfl_xor_f(d, 1); d += shfl_xor_f(d, 2); d += shfl_xor_f(d, 4); d += shfl_xor_f(d, 8);
;       if (dch == 0) sc_l[mm] = d * 0.08838834764831845f;
;     }
.LBB0_522:
	s_or_b64 exec, exec, s[8:9]
	v_add_u32_e32 v80, 20, v70
	s_waitcnt lgkmcnt(0)
	v_ashrrev_i32_e32 v81, 31, v80
	v_lshlrev_b64 v[80:81], 11, v[80:81]
	v_lshl_add_u64 v[84:85], v[68:69], 0, v[80:81]
	s_nop 0
	v_mbcnt_lo_u32_b32 v88, -1, 0
	v_mbcnt_hi_u32_b32 v88, -1, v88
	s_waitcnt vmcnt(4)
	v_mul_f32_e32 v81, v197, v78
	v_fmac_f32_e32 v81, v196, v67
	v_fmac_f32_e32 v81, v198, v71
	v_fmac_f32_e32 v81, v199, v73
	v_fmac_f32_e32 v81, v200, v74
	v_fmac_f32_e32 v81, v201, v75
	v_lshlrev_b32_e32 v88, 2, v88
	v_fmac_f32_e32 v81, v202, v76
	v_xor_b32_e32 v88, 4, v88
	v_fmac_f32_e32 v81, v203, v77
	ds_bpermute_b32 v80, v88, v81
	v_mbcnt_lo_u32_b32 v82, -1, 0
	v_mbcnt_hi_u32_b32 v82, -1, v82
	s_waitcnt lgkmcnt(0)
	v_add_f32_e32 v80, v81, v80
	v_lshlrev_b32_e32 v82, 2, v82
	v_xor_b32_e32 v82, 8, v82
	ds_bpermute_b32 v81, v82, v80
	v_mbcnt_lo_u32_b32 v82, -1, 0
	v_mbcnt_hi_u32_b32 v82, -1, v82
	s_waitcnt lgkmcnt(0)
	v_add_f32_e32 v80, v80, v81
	v_lshlrev_b32_e32 v82, 2, v82
	v_xor_b32_e32 v82, 16, v82
	ds_bpermute_b32 v81, v82, v80
	v_mbcnt_lo_u32_b32 v82, -1, 0
	v_mbcnt_hi_u32_b32 v82, -1, v82
	s_waitcnt lgkmcnt(0)
	v_add_f32_e32 v80, v80, v81
	v_lshlrev_b32_e32 v82, 2, v82
	v_xor_b32_e32 v81, 32, v82
	ds_bpermute_b32 v81, v81, v80
	s_and_saveexec_b64 s[8:9], vcc
	s_cbranch_execz .LBB0_524
	s_waitcnt lgkmcnt(0)
	v_add_f32_e32 v80, v80, v81
	v_mul_f32_e32 v80, 0x3db504f3, v80
	ds_write_b32 v79, v80 offset:80
.LBB0_524:
	s_or_b64 exec, exec, s[8:9]
	v_add_u32_e32 v80, 24, v70
	s_waitcnt lgkmcnt(0)
	v_ashrrev_i32_e32 v81, 31, v80
	v_lshlrev_b64 v[80:81], 11, v[80:81]
	v_lshl_add_u64 v[84:85], v[68:69], 0, v[80:81]
	s_nop 0
	v_mbcnt_lo_u32_b32 v88, -1, 0
	v_mbcnt_hi_u32_b32 v88, -1, v88
	s_waitcnt vmcnt(2)
	v_mul_f32_e32 v81, v205, v78
	v_fmac_f32_e32 v81, v204, v67
	v_fmac_f32_e32 v81, v206, v71
	v_fmac_f32_e32 v81, v207, v73
	v_fmac_f32_e32 v81, v208, v74
	v_fmac_f32_e32 v81, v209, v75
	v_lshlrev_b32_e32 v88, 2, v88
	v_fmac_f32_e32 v81, v210, v76
	v_xor_b32_e32 v88, 4, v88
	v_fmac_f32_e32 v81, v211, v77
	ds_bpermute_b32 v80, v88, v81
	v_mbcnt_lo_u32_b32 v82, -1, 0
	v_mbcnt_hi_u32_b32 v82, -1, v82
	s_waitcnt lgkmcnt(0)
	v_add_f32_e32 v80, v81, v80
	v_lshlrev_b32_e32 v82, 2, v82
	v_xor_b32_e32 v82, 8, v82
	ds_bpermute_b32 v81, v82, v80
	v_mbcnt_lo_u32_b32 v82, -1, 0
	v_mbcnt_hi_u32_b32 v82, -1, v82
	s_waitcnt lgkmcnt(0)
	v_add_f32_e32 v80, v80, v81
	v_lshlrev_b32_e32 v82, 2, v82
	v_xor_b32_e32 v82, 16, v82
	ds_bpermute_b32 v81, v82, v80
	v_mbcnt_lo_u32_b32 v82, -1, 0
	v_mbcnt_hi_u32_b32 v82, -1, v82
	s_waitcnt lgkmcnt(0)
	v_add_f32_e32 v80, v80, v81
	v_lshlrev_b32_e32 v82, 2, v82
	v_xor_b32_e32 v81, 32, v82
	ds_bpermute_b32 v81, v81, v80
	s_and_saveexec_b64 s[8:9], vcc
	s_cbranch_execz .LBB0_526
	s_waitcnt lgkmcnt(0)
	v_add_f32_e32 v80, v80, v81
	v_mul_f32_e32 v80, 0x3db504f3, v80
	ds_write_b32 v79, v80 offset:96
.LBB0_526:
	s_or_b64 exec, exec, s[8:9]
	v_add_u32_e32 v80, 28, v70
	s_waitcnt lgkmcnt(0)
	v_ashrrev_i32_e32 v81, 31, v80
	v_lshlrev_b64 v[80:81], 11, v[80:81]
	v_lshl_add_u64 v[68:69], v[68:69], 0, v[80:81]
	v_mbcnt_lo_u32_b32 v68, -1, 0
	v_mbcnt_hi_u32_b32 v68, -1, v68
	s_waitcnt vmcnt(0)
	v_mul_f32_e32 v69, v213, v78
	v_fmac_f32_e32 v69, v212, v67
	v_fmac_f32_e32 v69, v214, v71
	v_fmac_f32_e32 v69, v215, v73
	v_fmac_f32_e32 v69, v216, v74
	v_fmac_f32_e32 v69, v217, v75
	v_lshlrev_b32_e32 v68, 2, v68
	v_fmac_f32_e32 v69, v218, v76
	v_xor_b32_e32 v68, 4, v68
	v_fmac_f32_e32 v69, v219, v77
	ds_bpermute_b32 v67, v68, v69
	v_mbcnt_lo_u32_b32 v68, -1, 0
	v_mbcnt_hi_u32_b32 v68, -1, v68
	s_waitcnt lgkmcnt(0)
	v_add_f32_e32 v67, v69, v67
	v_lshlrev_b32_e32 v68, 2, v68
	v_xor_b32_e32 v68, 8, v68
	ds_bpermute_b32 v68, v68, v67
	v_mbcnt_lo_u32_b32 v69, -1, 0
	v_mbcnt_hi_u32_b32 v69, -1, v69
	s_waitcnt lgkmcnt(0)
	v_add_f32_e32 v67, v67, v68
	v_lshlrev_b32_e32 v69, 2, v69
	v_xor_b32_e32 v69, 16, v69
	ds_bpermute_b32 v68, v69, v67
	v_mbcnt_lo_u32_b32 v69, -1, 0
	v_mbcnt_hi_u32_b32 v69, -1, v69
	s_waitcnt lgkmcnt(0)
	v_add_f32_e32 v67, v67, v68
	v_lshlrev_b32_e32 v69, 2, v69
	v_xor_b32_e32 v68, 32, v69
	ds_bpermute_b32 v68, v68, v67
	s_and_saveexec_b64 s[8:9], vcc
	s_cbranch_execz .LBB0_528
	s_waitcnt lgkmcnt(0)
	v_add_f32_e32 v67, v67, v68
	v_mul_f32_e32 v67, 0x3db504f3, v67
	ds_write_b32 v79, v67 offset:112
